# C4 gated-merge GEMMs (NJ=1, fully unrolled) also converted to HBM->LDS direct loads with swizzled double-buffered LDS images
# speedup vs baseline: 1.0135x; 1.0135x over previous
; template <int NJ>
; DI void gemm_core(const h16* __restrict__ A, int lda, const h16* __restrict__ Bt, int ldb, int K,
;                   floatx16 (&acc)[2][NJ], h16* As, h16* Bs) {
;     ...
;   const h16* Ap = A + (size_t)(t >> 3) * lda + (t & 7) * 8;
;   const h16* Bp = Bt + (size_t)(t >> 3) * ldb + (t & 7) * 8;
;   const size_t sa = (size_t)32 * lda, sbb = (size_t)32 * ldb;
.LBB0_984:
	v_mov_b32_e32 v26, v152
	s_add_u32 s56, s90, s47
	v_ashrrev_i32_e32 v24, 3, v26
	v_ashrrev_i32_e32 v25, 31, v24
	v_lshlrev_b64 v[16:17], 11, v[24:25]
	v_lshlrev_b32_e32 v2, 4, v26
	v_lshl_add_u64 v[0:1], s[42:43], 0, v[16:17]
	v_and_b32_e32 v132, 0x70, v2
	v_lshl_add_u64 v[36:37], v[0:1], 0, v[132:133]
	v_add_co_u32_e32 v38, vcc, s55, v36
	v_and_b32_e32 v18, 7, v26
	s_nop 0
	v_addc_co_u32_e32 v39, vcc, 0, v37, vcc
	v_add_co_u32_e32 v40, vcc, s6, v36
	v_lshl_or_b32 v16, v18, 4, v16
	s_addc_u32 s57, s91, s53
	v_addc_co_u32_e32 v41, vcc, 0, v37, vcc
	v_lshl_add_u64 v[44:45], s[56:57], 0, v[16:17]
	v_add_co_u32_e32 v42, vcc, s7, v36
	s_nop 0
	v_addc_co_u32_e32 v43, vcc, 0, v37, vcc
	v_add_co_u32_e32 v46, vcc, s55, v44
	v_mad_u64_u32 v[32:33], s[56:57], v24, s67, v[132:133]
	s_nop 0
	v_addc_co_u32_e32 v47, vcc, 0, v45, vcc
	v_bfe_u32 v212, v152, 4, 3
	v_lshlrev_b32_e32 v212, 4, v212
	v_lshrrev_b32_e32 v213, 6, v152
	v_lshlrev_b32_e32 v213, 10, v213
	v_and_b32_e32 v214, 31, v152
	v_readfirstlane_b32 s100, v213
	v_bfe_u32 v215, v152, 5, 1
	v_bfe_u32 v216, v214, 1, 3
	v_xor_b32_e32 v216, v216, v215
	v_lshlrev_b32_e32 v216, 4, v216
	v_bfe_u32 v215, v152, 7, 1
	v_lshl_add_u32 v215, v215, 6, v214
	v_lshl_add_u32 v204, v215, 7, v216
	v_bfe_u32 v215, v152, 6, 1
	v_lshl_add_u32 v215, v215, 5, v214
	v_lshl_add_u32 v208, v215, 7, v216
	v_xor_b32_e32 v205, 32, v204
	v_xor_b32_e32 v206, 64, v204
	v_xor_b32_e32 v207, 0x60, v204
	v_xor_b32_e32 v209, 32, v208
	v_xor_b32_e32 v210, 64, v208
	v_xor_b32_e32 v211, 0x60, v208
	s_barrier
	s_add_u32 m0, s100, 2048
	v_xor_b32_e32 v36, v36, v212
	global_load_lds_dwordx4 v[36:37], off
	s_add_u32 m0, s100, 6144
	v_xor_b32_e32 v38, v38, v212
	global_load_lds_dwordx4 v[38:39], off
	s_add_u32 m0, s100, 10240
	v_xor_b32_e32 v40, v40, v212
	global_load_lds_dwordx4 v[40:41], off
	s_add_u32 m0, s100, 14336
	v_xor_b32_e32 v42, v42, v212
	global_load_lds_dwordx4 v[42:43], off
	s_add_u32 m0, s100, 18432
	v_xor_b32_e32 v44, v44, v212
	global_load_lds_dwordx4 v[44:45], off
	s_add_u32 m0, s100, 22528
	v_xor_b32_e32 v46, v46, v212
	global_load_lds_dwordx4 v[46:47], off
	s_waitcnt vmcnt(0)
	s_barrier
	s_add_u32 m0, s100, 41856
	s_nop 0
	global_load_lds_dwordx4 v[36:37], off offset:128
	s_add_u32 m0, s100, 45952
	s_nop 0
	global_load_lds_dwordx4 v[38:39], off offset:128
	s_add_u32 m0, s100, 50048
	s_nop 0
	global_load_lds_dwordx4 v[40:41], off offset:128
	s_add_u32 m0, s100, 54144
	s_nop 0
	global_load_lds_dwordx4 v[42:43], off offset:128
	s_add_u32 m0, s100, 58240
	s_nop 0
	global_load_lds_dwordx4 v[44:45], off offset:128
	s_add_u32 m0, s100, 62336
	s_nop 0
	global_load_lds_dwordx4 v[46:47], off offset:128
	v_and_b32_e32 v1, 31, v26
	v_lshrrev_b32_e32 v2, 1, v26
	v_and_or_b32 v3, v2, s8, v1
	v_and_b32_e32 v0, 16, v2
	v_and_or_b32 v1, v2, 32, v1
	v_mad_u64_u32 v[34:35], s[56:57], v3, s67, v[0:1]
	v_mad_u32_u24 v33, v1, s67, v0
	ds_read_b128 v[0:3], v204 offset:2048
	ds_read_b128 v[128:131], v205 offset:2048
	ds_read_b128 v[4:7], v204 offset:6144
	ds_read_b128 v[134:137], v205 offset:6144
	ds_read_b128 v[8:11], v208 offset:18432
	ds_read_b128 v[138:141], v209 offset:18432
	s_waitcnt lgkmcnt(1)
	v_mfma_f32_32x32x16_f16 v[16:31], v[0:3], v[8:11], 0
	v_mfma_f32_32x32x16_f16 v[0:15], v[4:7], v[8:11], 0
	ds_read_b128 v[142:145], v206 offset:6144
	ds_read_b128 v[146:149], v206 offset:2048
	ds_read_b128 v[166:169], v210 offset:18432
	s_waitcnt lgkmcnt(3)
	v_mfma_f32_32x32x16_f16 v[16:31], v[128:131], v[138:141], v[16:31]
	v_mfma_f32_32x32x16_f16 v[0:15], v[134:137], v[138:141], v[0:15]
	ds_read_b128 v[128:131], v207 offset:6144
	ds_read_b128 v[134:137], v207 offset:2048
	ds_read_b128 v[138:141], v211 offset:18432
	s_waitcnt lgkmcnt(3)
	v_mfma_f32_32x32x16_f16 v[16:31], v[146:149], v[166:169], v[16:31]
	v_mfma_f32_32x32x16_f16 v[0:15], v[142:145], v[166:169], v[0:15]
	s_waitcnt lgkmcnt(0)
	v_mfma_f32_32x32x16_f16 v[16:31], v[134:137], v[138:141], v[16:31]
	v_mfma_f32_32x32x16_f16 v[0:15], v[128:131], v[138:141], v[0:15]
	s_waitcnt vmcnt(0)
	s_barrier
	s_add_u32 m0, s100, 1792
	s_nop 0
	global_load_lds_dwordx4 v[36:37], off offset:256
	s_add_u32 m0, s100, 5888
	s_nop 0
	global_load_lds_dwordx4 v[38:39], off offset:256
	s_add_u32 m0, s100, 9984
	s_nop 0
	global_load_lds_dwordx4 v[40:41], off offset:256
	s_add_u32 m0, s100, 14080
	s_nop 0
	global_load_lds_dwordx4 v[42:43], off offset:256
	s_add_u32 m0, s100, 18176
	s_nop 0
	global_load_lds_dwordx4 v[44:45], off offset:256
	s_add_u32 m0, s100, 22272
	s_nop 0
	global_load_lds_dwordx4 v[46:47], off offset:256
	ds_read_b128 v[128:131], v204 offset:41984
	ds_read_b128 v[134:137], v205 offset:41984
	ds_read_b128 v[138:141], v204 offset:46080
	ds_read_b128 v[142:145], v205 offset:46080
	ds_read_b128 v[146:149], v208 offset:58368
	ds_read_b128 v[166:169], v209 offset:58368
	s_waitcnt lgkmcnt(1)
	v_mfma_f32_32x32x16_f16 v[16:31], v[128:131], v[146:149], v[16:31]
	v_mfma_f32_32x32x16_f16 v[0:15], v[138:141], v[146:149], v[0:15]
	ds_read_b128 v[128:131], v206 offset:46080
	ds_read_b128 v[138:141], v206 offset:41984
	ds_read_b128 v[146:149], v210 offset:58368
	s_waitcnt lgkmcnt(3)
	v_mfma_f32_32x32x16_f16 v[16:31], v[134:137], v[166:169], v[16:31]
	v_mfma_f32_32x32x16_f16 v[0:15], v[142:145], v[166:169], v[0:15]
	ds_read_b128 v[134:137], v207 offset:46080
	ds_read_b128 v[142:145], v207 offset:41984
	ds_read_b128 v[166:169], v211 offset:58368
	s_waitcnt lgkmcnt(3)
	v_mfma_f32_32x32x16_f16 v[16:31], v[138:141], v[146:149], v[16:31]
	v_mfma_f32_32x32x16_f16 v[0:15], v[128:131], v[146:149], v[0:15]
	s_waitcnt lgkmcnt(0)
	v_mfma_f32_32x32x16_f16 v[16:31], v[142:145], v[166:169], v[16:31]
	v_mfma_f32_32x32x16_f16 v[0:15], v[134:137], v[166:169], v[0:15]
	s_waitcnt vmcnt(0)
	s_barrier
	s_add_u32 m0, s100, 41600
	s_nop 0
	global_load_lds_dwordx4 v[36:37], off offset:384
	s_add_u32 m0, s100, 45696
	s_nop 0
	global_load_lds_dwordx4 v[38:39], off offset:384
	s_add_u32 m0, s100, 49792
	s_nop 0
	global_load_lds_dwordx4 v[40:41], off offset:384
	s_add_u32 m0, s100, 53888
	s_nop 0
	global_load_lds_dwordx4 v[42:43], off offset:384
	s_add_u32 m0, s100, 57984
	s_nop 0
	global_load_lds_dwordx4 v[44:45], off offset:384
	s_add_u32 m0, s100, 62080
	s_nop 0
	global_load_lds_dwordx4 v[46:47], off offset:384
	ds_read_b128 v[128:131], v204 offset:2048
	ds_read_b128 v[134:137], v205 offset:2048
	ds_read_b128 v[138:141], v204 offset:6144
	ds_read_b128 v[142:145], v205 offset:6144
	ds_read_b128 v[146:149], v208 offset:18432
	ds_read_b128 v[166:169], v209 offset:18432
	s_waitcnt lgkmcnt(1)
	v_mfma_f32_32x32x16_f16 v[16:31], v[128:131], v[146:149], v[16:31]
	v_mfma_f32_32x32x16_f16 v[0:15], v[138:141], v[146:149], v[0:15]
	ds_read_b128 v[128:131], v206 offset:6144
	ds_read_b128 v[138:141], v206 offset:2048
	ds_read_b128 v[146:149], v210 offset:18432
	s_waitcnt lgkmcnt(3)
	v_mfma_f32_32x32x16_f16 v[16:31], v[134:137], v[166:169], v[16:31]
	v_mfma_f32_32x32x16_f16 v[0:15], v[142:145], v[166:169], v[0:15]
	ds_read_b128 v[134:137], v207 offset:6144
	ds_read_b128 v[142:145], v207 offset:2048
	ds_read_b128 v[166:169], v211 offset:18432
	s_waitcnt lgkmcnt(3)
	v_mfma_f32_32x32x16_f16 v[16:31], v[138:141], v[146:149], v[16:31]
	v_mfma_f32_32x32x16_f16 v[0:15], v[128:131], v[146:149], v[0:15]
	s_waitcnt lgkmcnt(0)
	v_mfma_f32_32x32x16_f16 v[16:31], v[142:145], v[166:169], v[16:31]
	v_mfma_f32_32x32x16_f16 v[0:15], v[134:137], v[166:169], v[0:15]
	s_waitcnt vmcnt(0)
	s_barrier
	s_add_u32 m0, s100, 1536
	s_nop 0
	global_load_lds_dwordx4 v[36:37], off offset:512
	s_add_u32 m0, s100, 5632
	s_nop 0
	global_load_lds_dwordx4 v[38:39], off offset:512
	s_add_u32 m0, s100, 9728
	s_nop 0
	global_load_lds_dwordx4 v[40:41], off offset:512
	s_add_u32 m0, s100, 13824
	s_nop 0
	global_load_lds_dwordx4 v[42:43], off offset:512
	s_add_u32 m0, s100, 17920
	s_nop 0
	global_load_lds_dwordx4 v[44:45], off offset:512
	s_add_u32 m0, s100, 22016
	s_nop 0
	global_load_lds_dwordx4 v[46:47], off offset:512
	ds_read_b128 v[128:131], v204 offset:41984
	ds_read_b128 v[134:137], v205 offset:41984
	ds_read_b128 v[138:141], v204 offset:46080
	ds_read_b128 v[142:145], v205 offset:46080
	ds_read_b128 v[146:149], v208 offset:58368
	ds_read_b128 v[166:169], v209 offset:58368
	s_waitcnt lgkmcnt(1)
	v_mfma_f32_32x32x16_f16 v[16:31], v[128:131], v[146:149], v[16:31]
	v_mfma_f32_32x32x16_f16 v[0:15], v[138:141], v[146:149], v[0:15]
	ds_read_b128 v[128:131], v206 offset:46080
	ds_read_b128 v[138:141], v206 offset:41984
	ds_read_b128 v[146:149], v210 offset:58368
	s_waitcnt lgkmcnt(3)
	v_mfma_f32_32x32x16_f16 v[16:31], v[134:137], v[166:169], v[16:31]
	v_mfma_f32_32x32x16_f16 v[0:15], v[142:145], v[166:169], v[0:15]
	ds_read_b128 v[134:137], v207 offset:46080
	ds_read_b128 v[142:145], v207 offset:41984
	ds_read_b128 v[166:169], v211 offset:58368
	s_waitcnt lgkmcnt(3)
	v_mfma_f32_32x32x16_f16 v[16:31], v[138:141], v[146:149], v[16:31]
	v_mfma_f32_32x32x16_f16 v[0:15], v[128:131], v[146:149], v[0:15]
	s_waitcnt lgkmcnt(0)
	v_mfma_f32_32x32x16_f16 v[16:31], v[142:145], v[166:169], v[16:31]
	v_mfma_f32_32x32x16_f16 v[0:15], v[134:137], v[166:169], v[0:15]
	s_waitcnt vmcnt(0)
	s_barrier
	s_add_u32 m0, s100, 41344
	s_nop 0
	global_load_lds_dwordx4 v[36:37], off offset:640
	s_add_u32 m0, s100, 45440
	s_nop 0
	global_load_lds_dwordx4 v[38:39], off offset:640
	s_add_u32 m0, s100, 49536
	s_nop 0
	global_load_lds_dwordx4 v[40:41], off offset:640
	s_add_u32 m0, s100, 53632
	s_nop 0
	global_load_lds_dwordx4 v[42:43], off offset:640
	s_add_u32 m0, s100, 57728
	s_nop 0
	global_load_lds_dwordx4 v[44:45], off offset:640
	s_add_u32 m0, s100, 61824
	s_nop 0
	global_load_lds_dwordx4 v[46:47], off offset:640
	ds_read_b128 v[128:131], v204 offset:2048
	ds_read_b128 v[134:137], v205 offset:2048
	ds_read_b128 v[138:141], v204 offset:6144
	ds_read_b128 v[142:145], v205 offset:6144
	ds_read_b128 v[146:149], v208 offset:18432
	ds_read_b128 v[166:169], v209 offset:18432
	s_waitcnt lgkmcnt(1)
	v_mfma_f32_32x32x16_f16 v[16:31], v[128:131], v[146:149], v[16:31]
	v_mfma_f32_32x32x16_f16 v[0:15], v[138:141], v[146:149], v[0:15]
	ds_read_b128 v[128:131], v206 offset:6144
	ds_read_b128 v[138:141], v206 offset:2048
	ds_read_b128 v[146:149], v210 offset:18432
	s_waitcnt lgkmcnt(3)
	v_mfma_f32_32x32x16_f16 v[16:31], v[134:137], v[166:169], v[16:31]
	v_mfma_f32_32x32x16_f16 v[0:15], v[142:145], v[166:169], v[0:15]
	ds_read_b128 v[134:137], v207 offset:6144
	ds_read_b128 v[142:145], v207 offset:2048
	ds_read_b128 v[166:169], v211 offset:18432
	s_waitcnt lgkmcnt(3)
	v_mfma_f32_32x32x16_f16 v[16:31], v[138:141], v[146:149], v[16:31]
	v_mfma_f32_32x32x16_f16 v[0:15], v[128:131], v[146:149], v[0:15]
	s_waitcnt lgkmcnt(0)
	v_mfma_f32_32x32x16_f16 v[16:31], v[142:145], v[166:169], v[16:31]
	v_mfma_f32_32x32x16_f16 v[0:15], v[134:137], v[166:169], v[0:15]
	s_waitcnt vmcnt(0)
	s_barrier
; #define G_LOAD(RA, RB, k_) do { \
;     _Pragma("unroll") for (int i = 0; i < 4; ++i) RA[i] = *(const u32x4*)&Ap[i * sa + (k_)]; \
;     _Pragma("unroll") for (int i = 0; i < 2 * NJ; ++i) RB[i] = *(const u32x4*)&Bp[i * sbb + (k_)]; } while (0)
; template <int NJ>
; DI void gemm_core(const h16* __restrict__ A, int lda, const h16* __restrict__ Bt, int ldb, int K,
;                   floatx16 (&acc)[2][NJ], h16* As, h16* Bs) {
;     ...
;   G_LOAD(ra0, rb0, 0);
;   if (64 < K) G_LOAD(ra1, rb1, 64);
;   for (int k0 = 0; k0 < K; k0 += 128) {
;     G_STEP(ra0, rb0, k0 + 128);
;     if (k0 + 64 < K) G_STEP(ra1, rb1, k0 + 192);
;   }
	s_add_u32 m0, s100, 1280
	s_nop 0
	global_load_lds_dwordx4 v[36:37], off offset:768
	s_add_u32 m0, s100, 5376
	s_nop 0
	global_load_lds_dwordx4 v[38:39], off offset:768
	s_add_u32 m0, s100, 9472
	s_nop 0
	global_load_lds_dwordx4 v[40:41], off offset:768
	s_add_u32 m0, s100, 13568
	s_nop 0
	global_load_lds_dwordx4 v[42:43], off offset:768
	s_add_u32 m0, s100, 17664
	s_nop 0
	global_load_lds_dwordx4 v[44:45], off offset:768
	s_add_u32 m0, s100, 21760
	s_nop 0
	global_load_lds_dwordx4 v[46:47], off offset:768
	ds_read_b128 v[128:131], v204 offset:41984
	ds_read_b128 v[134:137], v205 offset:41984
	ds_read_b128 v[138:141], v204 offset:46080
	ds_read_b128 v[142:145], v205 offset:46080
	ds_read_b128 v[146:149], v208 offset:58368
	ds_read_b128 v[166:169], v209 offset:58368
	s_waitcnt lgkmcnt(1)
	v_mfma_f32_32x32x16_f16 v[16:31], v[128:131], v[146:149], v[16:31]
	v_mfma_f32_32x32x16_f16 v[0:15], v[138:141], v[146:149], v[0:15]
	ds_read_b128 v[128:131], v206 offset:46080
	ds_read_b128 v[138:141], v206 offset:41984
	ds_read_b128 v[146:149], v210 offset:58368
	s_waitcnt lgkmcnt(3)
	v_mfma_f32_32x32x16_f16 v[16:31], v[134:137], v[166:169], v[16:31]
	v_mfma_f32_32x32x16_f16 v[0:15], v[142:145], v[166:169], v[0:15]
	ds_read_b128 v[134:137], v207 offset:46080
	ds_read_b128 v[142:145], v207 offset:41984
	ds_read_b128 v[166:169], v211 offset:58368
	s_waitcnt lgkmcnt(3)
	v_mfma_f32_32x32x16_f16 v[16:31], v[138:141], v[146:149], v[16:31]
	v_mfma_f32_32x32x16_f16 v[0:15], v[128:131], v[146:149], v[0:15]
	s_waitcnt lgkmcnt(0)
	v_mfma_f32_32x32x16_f16 v[16:31], v[142:145], v[166:169], v[16:31]
	v_mfma_f32_32x32x16_f16 v[0:15], v[134:137], v[166:169], v[0:15]
	s_waitcnt vmcnt(0)
	s_barrier
	s_add_u32 m0, s100, 41088
	s_nop 0
	global_load_lds_dwordx4 v[36:37], off offset:896
	s_add_u32 m0, s100, 45184
	s_nop 0
	global_load_lds_dwordx4 v[38:39], off offset:896
	s_add_u32 m0, s100, 49280
	s_nop 0
	global_load_lds_dwordx4 v[40:41], off offset:896
	s_add_u32 m0, s100, 53376
	s_nop 0
	global_load_lds_dwordx4 v[42:43], off offset:896
	s_add_u32 m0, s100, 57472
	s_nop 0
	global_load_lds_dwordx4 v[44:45], off offset:896
	s_add_u32 m0, s100, 61568
	s_nop 0
	global_load_lds_dwordx4 v[46:47], off offset:896
	ds_read_b128 v[128:131], v204 offset:2048
	ds_read_b128 v[134:137], v205 offset:2048
	ds_read_b128 v[138:141], v204 offset:6144
	ds_read_b128 v[142:145], v205 offset:6144
	ds_read_b128 v[146:149], v208 offset:18432
	ds_read_b128 v[166:169], v209 offset:18432
	s_waitcnt lgkmcnt(1)
	v_mfma_f32_32x32x16_f16 v[16:31], v[128:131], v[146:149], v[16:31]
	v_mfma_f32_32x32x16_f16 v[0:15], v[138:141], v[146:149], v[0:15]
	ds_read_b128 v[128:131], v206 offset:6144
	ds_read_b128 v[138:141], v206 offset:2048
	ds_read_b128 v[146:149], v210 offset:18432
	s_waitcnt lgkmcnt(3)
	v_mfma_f32_32x32x16_f16 v[16:31], v[134:137], v[166:169], v[16:31]
	v_mfma_f32_32x32x16_f16 v[0:15], v[142:145], v[166:169], v[0:15]
	ds_read_b128 v[134:137], v207 offset:6144
	ds_read_b128 v[142:145], v207 offset:2048
	ds_read_b128 v[166:169], v211 offset:18432
	s_waitcnt lgkmcnt(3)
	v_mfma_f32_32x32x16_f16 v[16:31], v[138:141], v[146:149], v[16:31]
	v_mfma_f32_32x32x16_f16 v[0:15], v[128:131], v[146:149], v[0:15]
	s_waitcnt lgkmcnt(0)
	v_mfma_f32_32x32x16_f16 v[16:31], v[142:145], v[166:169], v[16:31]
	v_mfma_f32_32x32x16_f16 v[0:15], v[134:137], v[166:169], v[0:15]
	s_waitcnt vmcnt(0)
	s_barrier
	s_add_u32 m0, s100, 1024
	s_nop 0
	global_load_lds_dwordx4 v[36:37], off offset:1024
	s_add_u32 m0, s100, 5120
	s_nop 0
	global_load_lds_dwordx4 v[38:39], off offset:1024
	s_add_u32 m0, s100, 9216
	s_nop 0
	global_load_lds_dwordx4 v[40:41], off offset:1024
	s_add_u32 m0, s100, 13312
	s_nop 0
	global_load_lds_dwordx4 v[42:43], off offset:1024
	s_add_u32 m0, s100, 17408
	s_nop 0
	global_load_lds_dwordx4 v[44:45], off offset:1024
	s_add_u32 m0, s100, 21504
	s_nop 0
	global_load_lds_dwordx4 v[46:47], off offset:1024
	ds_read_b128 v[128:131], v204 offset:41984
	ds_read_b128 v[134:137], v205 offset:41984
	ds_read_b128 v[138:141], v204 offset:46080
	ds_read_b128 v[142:145], v205 offset:46080
	ds_read_b128 v[146:149], v208 offset:58368
	ds_read_b128 v[166:169], v209 offset:58368
	s_waitcnt lgkmcnt(1)
	v_mfma_f32_32x32x16_f16 v[16:31], v[128:131], v[146:149], v[16:31]
	v_mfma_f32_32x32x16_f16 v[0:15], v[138:141], v[146:149], v[0:15]
	ds_read_b128 v[128:131], v206 offset:46080
	ds_read_b128 v[138:141], v206 offset:41984
	ds_read_b128 v[146:149], v210 offset:58368
	s_waitcnt lgkmcnt(3)
	v_mfma_f32_32x32x16_f16 v[16:31], v[134:137], v[166:169], v[16:31]
	v_mfma_f32_32x32x16_f16 v[0:15], v[142:145], v[166:169], v[0:15]
	ds_read_b128 v[134:137], v207 offset:46080
	ds_read_b128 v[142:145], v207 offset:41984
	ds_read_b128 v[166:169], v211 offset:58368
	s_waitcnt lgkmcnt(3)
	v_mfma_f32_32x32x16_f16 v[16:31], v[138:141], v[146:149], v[16:31]
	v_mfma_f32_32x32x16_f16 v[0:15], v[128:131], v[146:149], v[0:15]
	s_waitcnt lgkmcnt(0)
	v_mfma_f32_32x32x16_f16 v[16:31], v[142:145], v[166:169], v[16:31]
	v_mfma_f32_32x32x16_f16 v[0:15], v[134:137], v[166:169], v[0:15]
	s_waitcnt vmcnt(0)
	s_barrier
; #define G_LOAD(RA, RB, k_) do { \
;     _Pragma("unroll") for (int i = 0; i < 4; ++i) RA[i] = *(const u32x4*)&Ap[i * sa + (k_)]; \
;     _Pragma("unroll") for (int i = 0; i < 2 * NJ; ++i) RB[i] = *(const u32x4*)&Bp[i * sbb + (k_)]; } while (0)
; template <int NJ>
; DI void gemm_core(const h16* __restrict__ A, int lda, const h16* __restrict__ Bt, int ldb, int K,
;                   floatx16 (&acc)[2][NJ], h16* As, h16* Bs) {
;     ...
;   G_LOAD(ra0, rb0, 0);
;   if (64 < K) G_LOAD(ra1, rb1, 64);
;   for (int k0 = 0; k0 < K; k0 += 128) {
;     G_STEP(ra0, rb0, k0 + 128);
;     if (k0 + 64 < K) G_STEP(ra1, rb1, k0 + 192);
;   }
	s_add_u32 m0, s100, 40832
	s_nop 0
	global_load_lds_dwordx4 v[36:37], off offset:1152
	s_add_u32 m0, s100, 44928
	s_nop 0
	global_load_lds_dwordx4 v[38:39], off offset:1152
	s_add_u32 m0, s100, 49024
	s_nop 0
	global_load_lds_dwordx4 v[40:41], off offset:1152
	s_add_u32 m0, s100, 53120
	s_nop 0
	global_load_lds_dwordx4 v[42:43], off offset:1152
	s_add_u32 m0, s100, 57216
	s_nop 0
	global_load_lds_dwordx4 v[44:45], off offset:1152
	s_add_u32 m0, s100, 61312
	s_nop 0
	global_load_lds_dwordx4 v[46:47], off offset:1152
	ds_read_b128 v[128:131], v204 offset:2048
	ds_read_b128 v[134:137], v205 offset:2048
	ds_read_b128 v[138:141], v204 offset:6144
	ds_read_b128 v[142:145], v205 offset:6144
	ds_read_b128 v[146:149], v208 offset:18432
	ds_read_b128 v[166:169], v209 offset:18432
	s_waitcnt lgkmcnt(1)
	v_mfma_f32_32x32x16_f16 v[16:31], v[128:131], v[146:149], v[16:31]
	v_mfma_f32_32x32x16_f16 v[0:15], v[138:141], v[146:149], v[0:15]
	ds_read_b128 v[128:131], v206 offset:6144
	ds_read_b128 v[138:141], v206 offset:2048
	ds_read_b128 v[146:149], v210 offset:18432
	s_waitcnt lgkmcnt(3)
	v_mfma_f32_32x32x16_f16 v[16:31], v[134:137], v[166:169], v[16:31]
	v_mfma_f32_32x32x16_f16 v[0:15], v[142:145], v[166:169], v[0:15]
	ds_read_b128 v[134:137], v207 offset:6144
	ds_read_b128 v[142:145], v207 offset:2048
	ds_read_b128 v[166:169], v211 offset:18432
	s_waitcnt lgkmcnt(3)
	v_mfma_f32_32x32x16_f16 v[16:31], v[138:141], v[146:149], v[16:31]
	v_mfma_f32_32x32x16_f16 v[0:15], v[128:131], v[146:149], v[0:15]
	s_waitcnt lgkmcnt(0)
	v_mfma_f32_32x32x16_f16 v[16:31], v[142:145], v[166:169], v[16:31]
	v_mfma_f32_32x32x16_f16 v[0:15], v[134:137], v[166:169], v[0:15]
	s_waitcnt vmcnt(0)
	s_barrier
	s_add_u32 m0, s100, 768
	s_nop 0
	global_load_lds_dwordx4 v[36:37], off offset:1280
	s_add_u32 m0, s100, 4864
	s_nop 0
	global_load_lds_dwordx4 v[38:39], off offset:1280
	s_add_u32 m0, s100, 8960
	s_nop 0
	global_load_lds_dwordx4 v[40:41], off offset:1280
	s_add_u32 m0, s100, 13056
	s_nop 0
	global_load_lds_dwordx4 v[42:43], off offset:1280
	s_add_u32 m0, s100, 17152
	s_nop 0
	global_load_lds_dwordx4 v[44:45], off offset:1280
	s_add_u32 m0, s100, 21248
	s_nop 0
	global_load_lds_dwordx4 v[46:47], off offset:1280
	ds_read_b128 v[128:131], v204 offset:41984
	ds_read_b128 v[134:137], v205 offset:41984
	ds_read_b128 v[138:141], v204 offset:46080
	ds_read_b128 v[142:145], v205 offset:46080
	ds_read_b128 v[146:149], v208 offset:58368
	ds_read_b128 v[166:169], v209 offset:58368
	s_waitcnt lgkmcnt(1)
	v_mfma_f32_32x32x16_f16 v[16:31], v[128:131], v[146:149], v[16:31]
	v_mfma_f32_32x32x16_f16 v[0:15], v[138:141], v[146:149], v[0:15]
	ds_read_b128 v[128:131], v206 offset:46080
	ds_read_b128 v[138:141], v206 offset:41984
	ds_read_b128 v[146:149], v210 offset:58368
	s_waitcnt lgkmcnt(3)
	v_mfma_f32_32x32x16_f16 v[16:31], v[134:137], v[166:169], v[16:31]
	v_mfma_f32_32x32x16_f16 v[0:15], v[142:145], v[166:169], v[0:15]
	ds_read_b128 v[134:137], v207 offset:46080
	ds_read_b128 v[142:145], v207 offset:41984
	ds_read_b128 v[166:169], v211 offset:58368
	s_waitcnt lgkmcnt(3)
	v_mfma_f32_32x32x16_f16 v[16:31], v[138:141], v[146:149], v[16:31]
	v_mfma_f32_32x32x16_f16 v[0:15], v[128:131], v[146:149], v[0:15]
	s_waitcnt lgkmcnt(0)
	v_mfma_f32_32x32x16_f16 v[16:31], v[142:145], v[166:169], v[16:31]
	v_mfma_f32_32x32x16_f16 v[0:15], v[134:137], v[166:169], v[0:15]
	s_waitcnt vmcnt(0)
	s_barrier
	s_add_u32 m0, s100, 40576
	s_nop 0
	global_load_lds_dwordx4 v[36:37], off offset:1408
	s_add_u32 m0, s100, 44672
	s_nop 0
	global_load_lds_dwordx4 v[38:39], off offset:1408
	s_add_u32 m0, s100, 48768
	s_nop 0
	global_load_lds_dwordx4 v[40:41], off offset:1408
	s_add_u32 m0, s100, 52864
	s_nop 0
	global_load_lds_dwordx4 v[42:43], off offset:1408
	s_add_u32 m0, s100, 56960
	s_nop 0
	global_load_lds_dwordx4 v[44:45], off offset:1408
	s_add_u32 m0, s100, 61056
	s_nop 0
	global_load_lds_dwordx4 v[46:47], off offset:1408
	ds_read_b128 v[128:131], v204 offset:2048
	ds_read_b128 v[134:137], v205 offset:2048
	ds_read_b128 v[138:141], v204 offset:6144
	ds_read_b128 v[142:145], v205 offset:6144
	ds_read_b128 v[146:149], v208 offset:18432
	ds_read_b128 v[166:169], v209 offset:18432
	s_waitcnt lgkmcnt(1)
	v_mfma_f32_32x32x16_f16 v[16:31], v[128:131], v[146:149], v[16:31]
	v_mfma_f32_32x32x16_f16 v[0:15], v[138:141], v[146:149], v[0:15]
	ds_read_b128 v[128:131], v206 offset:6144
	ds_read_b128 v[138:141], v206 offset:2048
	ds_read_b128 v[146:149], v210 offset:18432
	s_waitcnt lgkmcnt(3)
	v_mfma_f32_32x32x16_f16 v[16:31], v[134:137], v[166:169], v[16:31]
	v_mfma_f32_32x32x16_f16 v[0:15], v[142:145], v[166:169], v[0:15]
	ds_read_b128 v[134:137], v207 offset:6144
	ds_read_b128 v[142:145], v207 offset:2048
	ds_read_b128 v[166:169], v211 offset:18432
	s_waitcnt lgkmcnt(3)
	v_mfma_f32_32x32x16_f16 v[16:31], v[138:141], v[146:149], v[16:31]
	v_mfma_f32_32x32x16_f16 v[0:15], v[128:131], v[146:149], v[0:15]
	s_waitcnt lgkmcnt(0)
	v_mfma_f32_32x32x16_f16 v[16:31], v[142:145], v[166:169], v[16:31]
	v_mfma_f32_32x32x16_f16 v[0:15], v[134:137], v[166:169], v[0:15]
	s_waitcnt vmcnt(0)
	s_barrier
; #define G_LOAD(RA, RB, k_) do { \
;     _Pragma("unroll") for (int i = 0; i < 4; ++i) RA[i] = *(const u32x4*)&Ap[i * sa + (k_)]; \
;     _Pragma("unroll") for (int i = 0; i < 2 * NJ; ++i) RB[i] = *(const u32x4*)&Bp[i * sbb + (k_)]; } while (0)
; template <int NJ>
; DI void gemm_core(const h16* __restrict__ A, int lda, const h16* __restrict__ Bt, int ldb, int K,
;                   floatx16 (&acc)[2][NJ], h16* As, h16* Bs) {
;     ...
;   G_LOAD(ra0, rb0, 0);
;   if (64 < K) G_LOAD(ra1, rb1, 64);
;   for (int k0 = 0; k0 < K; k0 += 128) {
;     G_STEP(ra0, rb0, k0 + 128);
;     if (k0 + 64 < K) G_STEP(ra1, rb1, k0 + 192);
;   }
	s_add_u32 m0, s100, 512
	s_nop 0
	global_load_lds_dwordx4 v[36:37], off offset:1536
	s_add_u32 m0, s100, 4608
	s_nop 0
	global_load_lds_dwordx4 v[38:39], off offset:1536
	s_add_u32 m0, s100, 8704
	s_nop 0
	global_load_lds_dwordx4 v[40:41], off offset:1536
	s_add_u32 m0, s100, 12800
	s_nop 0
	global_load_lds_dwordx4 v[42:43], off offset:1536
	s_add_u32 m0, s100, 16896
	s_nop 0
	global_load_lds_dwordx4 v[44:45], off offset:1536
	s_add_u32 m0, s100, 20992
	s_nop 0
	global_load_lds_dwordx4 v[46:47], off offset:1536
	ds_read_b128 v[128:131], v204 offset:41984
	ds_read_b128 v[134:137], v205 offset:41984
	ds_read_b128 v[138:141], v204 offset:46080
	ds_read_b128 v[142:145], v205 offset:46080
	ds_read_b128 v[146:149], v208 offset:58368
	ds_read_b128 v[166:169], v209 offset:58368
	s_waitcnt lgkmcnt(1)
	v_mfma_f32_32x32x16_f16 v[16:31], v[128:131], v[146:149], v[16:31]
	v_mfma_f32_32x32x16_f16 v[0:15], v[138:141], v[146:149], v[0:15]
	ds_read_b128 v[128:131], v206 offset:46080
	ds_read_b128 v[138:141], v206 offset:41984
	ds_read_b128 v[146:149], v210 offset:58368
	s_waitcnt lgkmcnt(3)
	v_mfma_f32_32x32x16_f16 v[16:31], v[134:137], v[166:169], v[16:31]
	v_mfma_f32_32x32x16_f16 v[0:15], v[142:145], v[166:169], v[0:15]
	ds_read_b128 v[134:137], v207 offset:46080
	ds_read_b128 v[142:145], v207 offset:41984
	ds_read_b128 v[166:169], v211 offset:58368
	s_waitcnt lgkmcnt(3)
	v_mfma_f32_32x32x16_f16 v[16:31], v[138:141], v[146:149], v[16:31]
	v_mfma_f32_32x32x16_f16 v[0:15], v[128:131], v[146:149], v[0:15]
	s_waitcnt lgkmcnt(0)
	v_mfma_f32_32x32x16_f16 v[16:31], v[142:145], v[166:169], v[16:31]
	v_mfma_f32_32x32x16_f16 v[0:15], v[134:137], v[166:169], v[0:15]
	s_waitcnt vmcnt(0)
	s_barrier
	s_add_u32 m0, s100, 40320
	s_nop 0
	global_load_lds_dwordx4 v[36:37], off offset:1664
	s_add_u32 m0, s100, 44416
	s_nop 0
	global_load_lds_dwordx4 v[38:39], off offset:1664
	s_add_u32 m0, s100, 48512
	s_nop 0
	global_load_lds_dwordx4 v[40:41], off offset:1664
	s_add_u32 m0, s100, 52608
	s_nop 0
	global_load_lds_dwordx4 v[42:43], off offset:1664
	s_add_u32 m0, s100, 56704
	s_nop 0
	global_load_lds_dwordx4 v[44:45], off offset:1664
	s_add_u32 m0, s100, 60800
	s_nop 0
	global_load_lds_dwordx4 v[46:47], off offset:1664
	ds_read_b128 v[128:131], v204 offset:2048
	ds_read_b128 v[134:137], v205 offset:2048
	ds_read_b128 v[138:141], v204 offset:6144
	ds_read_b128 v[142:145], v205 offset:6144
	ds_read_b128 v[146:149], v208 offset:18432
	ds_read_b128 v[166:169], v209 offset:18432
	s_waitcnt lgkmcnt(1)
	v_mfma_f32_32x32x16_f16 v[16:31], v[128:131], v[146:149], v[16:31]
	v_mfma_f32_32x32x16_f16 v[0:15], v[138:141], v[146:149], v[0:15]
	ds_read_b128 v[128:131], v206 offset:6144
	ds_read_b128 v[138:141], v206 offset:2048
	ds_read_b128 v[146:149], v210 offset:18432
	s_waitcnt lgkmcnt(3)
	v_mfma_f32_32x32x16_f16 v[16:31], v[134:137], v[166:169], v[16:31]
	v_mfma_f32_32x32x16_f16 v[0:15], v[142:145], v[166:169], v[0:15]
	ds_read_b128 v[134:137], v207 offset:6144
	ds_read_b128 v[142:145], v207 offset:2048
	ds_read_b128 v[166:169], v211 offset:18432
	s_waitcnt lgkmcnt(3)
	v_mfma_f32_32x32x16_f16 v[16:31], v[138:141], v[146:149], v[16:31]
	v_mfma_f32_32x32x16_f16 v[0:15], v[128:131], v[146:149], v[0:15]
	s_waitcnt lgkmcnt(0)
	v_mfma_f32_32x32x16_f16 v[16:31], v[142:145], v[166:169], v[16:31]
	v_mfma_f32_32x32x16_f16 v[0:15], v[134:137], v[166:169], v[0:15]
	s_waitcnt vmcnt(0)
	s_barrier
	s_add_u32 m0, s100, 256
	s_nop 0
	global_load_lds_dwordx4 v[36:37], off offset:1792
	s_add_u32 m0, s100, 4352
	s_nop 0
	global_load_lds_dwordx4 v[38:39], off offset:1792
	s_add_u32 m0, s100, 8448
	s_nop 0
	global_load_lds_dwordx4 v[40:41], off offset:1792
	s_add_u32 m0, s100, 12544
	s_nop 0
	global_load_lds_dwordx4 v[42:43], off offset:1792
	s_add_u32 m0, s100, 16640
	s_nop 0
	global_load_lds_dwordx4 v[44:45], off offset:1792
	s_add_u32 m0, s100, 20736
	s_nop 0
	global_load_lds_dwordx4 v[46:47], off offset:1792
	s_nop 0
	s_nop 0
	s_nop 0
	s_nop 0
	s_nop 0
	ds_read_b128 v[60:63], v204 offset:41984
	ds_read_b128 v[96:99], v205 offset:41984
	ds_read_b128 v[100:103], v204 offset:46080
	ds_read_b128 v[128:131], v205 offset:46080
	ds_read_b128 v[134:137], v208 offset:58368
	ds_read_b128 v[138:141], v209 offset:58368
	s_waitcnt lgkmcnt(1)
	v_mfma_f32_32x32x16_f16 v[16:31], v[60:63], v[134:137], v[16:31]
	v_mfma_f32_32x32x16_f16 v[0:15], v[100:103], v[134:137], v[0:15]
	ds_read_b128 v[60:63], v206 offset:46080
	ds_read_b128 v[100:103], v206 offset:41984
	ds_read_b128 v[134:137], v210 offset:58368
	s_waitcnt lgkmcnt(3)
	v_mfma_f32_32x32x16_f16 v[16:31], v[96:99], v[138:141], v[16:31]
	v_mfma_f32_32x32x16_f16 v[0:15], v[128:131], v[138:141], v[0:15]
	ds_read_b128 v[96:99], v207 offset:46080
	ds_read_b128 v[128:131], v207 offset:41984
	ds_read_b128 v[138:141], v211 offset:58368
	s_waitcnt lgkmcnt(3)
	v_mfma_f32_32x32x16_f16 v[16:31], v[100:103], v[134:137], v[16:31]
	v_mfma_f32_32x32x16_f16 v[0:15], v[60:63], v[134:137], v[0:15]
	s_waitcnt lgkmcnt(0)
	v_mfma_f32_32x32x16_f16 v[16:31], v[128:131], v[138:141], v[16:31]
	v_mfma_f32_32x32x16_f16 v[0:15], v[96:99], v[138:141], v[0:15]
	s_waitcnt vmcnt(0)
	s_barrier
; #define G_LOAD(RA, RB, k_) do { \
;     _Pragma("unroll") for (int i = 0; i < 4; ++i) RA[i] = *(const u32x4*)&Ap[i * sa + (k_)]; \
;     _Pragma("unroll") for (int i = 0; i < 2 * NJ; ++i) RB[i] = *(const u32x4*)&Bp[i * sbb + (k_)]; } while (0)
; template <int NJ>
; DI void gemm_core(const h16* __restrict__ A, int lda, const h16* __restrict__ Bt, int ldb, int K,
;                   floatx16 (&acc)[2][NJ], h16* As, h16* Bs) {
;     ...
;   G_LOAD(ra0, rb0, 0);
;   if (64 < K) G_LOAD(ra1, rb1, 64);
;   for (int k0 = 0; k0 < K; k0 += 128) {
;     G_STEP(ra0, rb0, k0 + 128);
;     if (k0 + 64 < K) G_STEP(ra1, rb1, k0 + 192);
;   }
; __global__ void __launch_bounds__(256, 2) mega(Params p) {
;     ...
;       for (int b = 0; b < 3; ++b) {
;         floatx16 ag[2][1]; acc_zero<1>(ag);
;         gemm_core<1>(x16 + (size_t)m0 * 1024, 1024, Wt + WT_IN + (size_t)(3200 + 1024 * b + n0) * 1024, 1024, 1024, ag, As, Bs);
;         floatx16 ap[2][1]; acc_zero<1>(ap);
;         const h16* br = b == 0 ? aout : (b == 1 ? bout : cout_);
;         gemm_core<1>(br + (size_t)m0 * 512, 512, Wt + WT_BR + (size_t)(b * 1024 + n0) * 512, 512, 512, ap, As, Bs);
	s_add_u32 m0, s100, 40064
	s_nop 0
	global_load_lds_dwordx4 v[36:37], off offset:1920
	s_add_u32 m0, s100, 44160
	s_nop 0
	global_load_lds_dwordx4 v[38:39], off offset:1920
	s_add_u32 m0, s100, 48256
	s_nop 0
	global_load_lds_dwordx4 v[40:41], off offset:1920
	s_add_u32 m0, s100, 52352
	s_nop 0
	global_load_lds_dwordx4 v[42:43], off offset:1920
	s_add_u32 m0, s100, 56448
	s_nop 0
	global_load_lds_dwordx4 v[44:45], off offset:1920
	s_add_u32 m0, s100, 60544
	s_nop 0
	global_load_lds_dwordx4 v[46:47], off offset:1920
	ds_read_b128 v[60:63], v204 offset:2048
	ds_read_b128 v[96:99], v205 offset:2048
	ds_read_b128 v[100:103], v204 offset:6144
	ds_read_b128 v[104:107], v205 offset:6144
	ds_read_b128 v[108:111], v208 offset:18432
	ds_read_b128 v[112:115], v209 offset:18432
	s_waitcnt lgkmcnt(1)
	v_mfma_f32_32x32x16_f16 v[16:31], v[60:63], v[108:111], v[16:31]
	v_mfma_f32_32x32x16_f16 v[0:15], v[100:103], v[108:111], v[0:15]
	ds_read_b128 v[60:63], v206 offset:6144
	ds_read_b128 v[100:103], v206 offset:2048
	ds_read_b128 v[108:111], v210 offset:18432
	s_waitcnt lgkmcnt(3)
	v_mfma_f32_32x32x16_f16 v[16:31], v[96:99], v[112:115], v[16:31]
	v_mfma_f32_32x32x16_f16 v[0:15], v[104:107], v[112:115], v[0:15]
	ds_read_b128 v[96:99], v207 offset:6144
	ds_read_b128 v[104:107], v207 offset:2048
	ds_read_b128 v[112:115], v211 offset:18432
	s_waitcnt lgkmcnt(3)
	v_mfma_f32_32x32x16_f16 v[16:31], v[100:103], v[108:111], v[16:31]
	v_mfma_f32_32x32x16_f16 v[0:15], v[60:63], v[108:111], v[0:15]
	s_waitcnt lgkmcnt(0)
	v_mfma_f32_32x32x16_f16 v[16:31], v[104:107], v[112:115], v[16:31]
	v_mfma_f32_32x32x16_f16 v[0:15], v[96:99], v[112:115], v[0:15]
	s_waitcnt vmcnt(0)
	s_barrier
	ds_read_b128 v[36:39], v204 offset:41984
	ds_read_b128 v[40:43], v205 offset:41984
	ds_read_b128 v[44:47], v204 offset:46080
	ds_read_b128 v[48:51], v205 offset:46080
	ds_read_b128 v[52:55], v208 offset:58368
	ds_read_b128 v[56:59], v209 offset:58368
	s_waitcnt lgkmcnt(1)
	v_mfma_f32_32x32x16_f16 v[16:31], v[36:39], v[52:55], v[16:31]
	v_mfma_f32_32x32x16_f16 v[0:15], v[44:47], v[52:55], v[0:15]
	ds_read_b128 v[36:39], v206 offset:46080
	ds_read_b128 v[44:47], v206 offset:41984
	ds_read_b128 v[52:55], v210 offset:58368
	s_waitcnt lgkmcnt(3)
	v_mfma_f32_32x32x16_f16 v[16:31], v[40:43], v[56:59], v[16:31]
	v_mfma_f32_32x32x16_f16 v[0:15], v[48:51], v[56:59], v[0:15]
	ds_read_b128 v[40:43], v207 offset:46080
	ds_read_b128 v[48:51], v207 offset:41984
	ds_read_b128 v[32:35], v211 offset:58368
	s_waitcnt lgkmcnt(3)
	v_mfma_f32_32x32x16_f16 v[16:31], v[44:47], v[52:55], v[16:31]
	v_mfma_f32_32x32x16_f16 v[0:15], v[36:39], v[52:55], v[0:15]
	s_waitcnt lgkmcnt(0)
	v_mfma_f32_32x32x16_f16 v[16:31], v[48:51], v[32:35], v[16:31]
	v_mfma_f32_32x32x16_f16 v[0:15], v[40:43], v[32:35], v[0:15]
	s_cmp_eq_u32 s64, 1
	v_readlane_b32 s10, v234, 35
	s_cselect_b32 s56, s10, s38
	v_readlane_b32 s10, v234, 36
	s_cselect_b32 s57, s10, s39
	s_cmp_eq_u32 s64, 0
	v_mov_b32_e32 v58, v152
	s_cselect_b32 s56, s4, s56
	s_cselect_b32 s57, s5, s57
	v_ashrrev_i32_e32 v56, 3, v58
	s_add_u32 s56, s56, s61
	v_ashrrev_i32_e32 v57, 31, v56
	s_addc_u32 s57, s57, 0
	v_lshlrev_b64 v[48:49], 10, v[56:57]
	v_lshlrev_b32_e32 v34, 4, v58
	v_lshl_add_u64 v[32:33], s[56:57], 0, v[48:49]
	v_and_b32_e32 v132, 0x70, v34
	v_lshl_add_u64 v[100:101], v[32:33], 0, v[132:133]
	v_add_co_u32_e32 v102, vcc, s81, v100
	v_and_b32_e32 v50, 7, v58
	s_nop 0
	v_addc_co_u32_e32 v103, vcc, 0, v101, vcc
	v_add_co_u32_e32 v104, vcc, s55, v100
	s_add_u32 s56, s90, s44
	s_nop 0
	v_addc_co_u32_e32 v105, vcc, 0, v101, vcc
	v_add_co_u32_e32 v106, vcc, s9, v100
	v_lshl_or_b32 v48, v50, 4, v48
	s_addc_u32 s57, s91, s45
	v_addc_co_u32_e32 v107, vcc, 0, v101, vcc
	v_lshl_add_u64 v[52:53], s[56:57], 0, v[48:49]
	s_mov_b32 s56, 0xc40000
	v_add_co_u32_e32 v108, vcc, s56, v52
	v_addc_co_u32_e32 v109, vcc, 0, v53, vcc
	s_mov_b32 s56, 0xc48000
	v_add_co_u32_e32 v110, vcc, s56, v52
	s_nop 0
	v_addc_co_u32_e32 v111, vcc, 0, v53, vcc
	v_mad_u64_u32 v[96:97], s[56:57], v56, s67, v[132:133]
	v_bfe_u32 v212, v152, 4, 3
	v_lshlrev_b32_e32 v212, 4, v212
	v_lshrrev_b32_e32 v213, 6, v152
	v_lshlrev_b32_e32 v213, 10, v213
	v_and_b32_e32 v214, 31, v152
	v_readfirstlane_b32 s100, v213
	v_bfe_u32 v215, v152, 5, 1
	v_bfe_u32 v216, v214, 1, 3
	v_xor_b32_e32 v216, v216, v215
	v_lshlrev_b32_e32 v216, 4, v216
	v_bfe_u32 v215, v152, 7, 1
	v_lshl_add_u32 v215, v215, 6, v214
	v_lshl_add_u32 v204, v215, 7, v216
	v_bfe_u32 v215, v152, 6, 1
	v_lshl_add_u32 v215, v215, 5, v214
	v_lshl_add_u32 v208, v215, 7, v216
	v_xor_b32_e32 v205, 32, v204
	v_xor_b32_e32 v206, 64, v204
	v_xor_b32_e32 v207, 0x60, v204
	v_xor_b32_e32 v209, 32, v208
	v_xor_b32_e32 v210, 64, v208
	v_xor_b32_e32 v211, 0x60, v208
	s_barrier
	s_add_u32 m0, s100, 2048
	v_xor_b32_e32 v100, v100, v212
	global_load_lds_dwordx4 v[100:101], off
	s_add_u32 m0, s100, 6144
	v_xor_b32_e32 v102, v102, v212
	global_load_lds_dwordx4 v[102:103], off
	s_add_u32 m0, s100, 10240
	v_xor_b32_e32 v104, v104, v212
	global_load_lds_dwordx4 v[104:105], off
	s_add_u32 m0, s100, 14336
	v_xor_b32_e32 v106, v106, v212
	global_load_lds_dwordx4 v[106:107], off
	s_add_u32 m0, s100, 18432
	v_xor_b32_e32 v108, v108, v212
	global_load_lds_dwordx4 v[108:109], off
	s_add_u32 m0, s100, 22528
	v_xor_b32_e32 v110, v110, v212
	global_load_lds_dwordx4 v[110:111], off
	s_waitcnt vmcnt(0)
	s_barrier
; #define G_LOAD(RA, RB, k_) do { \
;     _Pragma("unroll") for (int i = 0; i < 4; ++i) RA[i] = *(const u32x4*)&Ap[i * sa + (k_)]; \
;     _Pragma("unroll") for (int i = 0; i < 2 * NJ; ++i) RB[i] = *(const u32x4*)&Bp[i * sbb + (k_)]; } while (0)
; template <int NJ>
; DI void gemm_core(const h16* __restrict__ A, int lda, const h16* __restrict__ Bt, int ldb, int K,
;                   floatx16 (&acc)[2][NJ], h16* As, h16* Bs) {
;     ...
;   G_LOAD(ra0, rb0, 0);
;   if (64 < K) G_LOAD(ra1, rb1, 64);
;   for (int k0 = 0; k0 < K; k0 += 128) {
;     G_STEP(ra0, rb0, k0 + 128);
;     if (k0 + 64 < K) G_STEP(ra1, rb1, k0 + 192);
;   }
	s_add_u32 m0, s100, 41856
	s_nop 0
	global_load_lds_dwordx4 v[100:101], off offset:128
	s_add_u32 m0, s100, 45952
	s_nop 0
	global_load_lds_dwordx4 v[102:103], off offset:128
	s_add_u32 m0, s100, 50048
	s_nop 0
	global_load_lds_dwordx4 v[104:105], off offset:128
	s_add_u32 m0, s100, 54144
	s_nop 0
	global_load_lds_dwordx4 v[106:107], off offset:128
	s_add_u32 m0, s100, 58240
	s_nop 0
	global_load_lds_dwordx4 v[108:109], off offset:128
	s_add_u32 m0, s100, 62336
	s_nop 0
	global_load_lds_dwordx4 v[110:111], off offset:128
	v_and_b32_e32 v33, 31, v58
	v_lshrrev_b32_e32 v34, 1, v58
	v_and_or_b32 v35, v34, s8, v33
	v_and_b32_e32 v32, 16, v34
	v_and_or_b32 v33, v34, 32, v33
	v_mad_u64_u32 v[98:99], s[56:57], v35, s67, v[32:33]
	v_mad_u32_u24 v132, v33, s67, v32
	ds_read_b128 v[32:35], v204 offset:2048
	ds_read_b128 v[178:181], v205 offset:2048
	ds_read_b128 v[36:39], v204 offset:6144
	ds_read_b128 v[182:185], v205 offset:6144
	ds_read_b128 v[40:43], v208 offset:18432
	ds_read_b128 v[186:189], v209 offset:18432
	s_waitcnt lgkmcnt(1)
	v_mfma_f32_32x32x16_f16 v[48:63], v[32:35], v[40:43], 0
	v_mfma_f32_32x32x16_f16 v[32:47], v[36:39], v[40:43], 0
	ds_read_b128 v[190:193], v206 offset:6144
	ds_read_b128 v[194:197], v206 offset:2048
	ds_read_b128 v[198:201], v210 offset:18432
	s_waitcnt lgkmcnt(3)
	v_mfma_f32_32x32x16_f16 v[48:63], v[178:181], v[186:189], v[48:63]
	v_mfma_f32_32x32x16_f16 v[32:47], v[182:185], v[186:189], v[32:47]
	ds_read_b128 v[178:181], v207 offset:6144
	ds_read_b128 v[182:185], v207 offset:2048
	ds_read_b128 v[186:189], v211 offset:18432
	s_waitcnt lgkmcnt(3)
	v_mfma_f32_32x32x16_f16 v[48:63], v[194:197], v[198:201], v[48:63]
	v_mfma_f32_32x32x16_f16 v[32:47], v[190:193], v[198:201], v[32:47]
	s_waitcnt lgkmcnt(0)
	v_mfma_f32_32x32x16_f16 v[48:63], v[182:185], v[186:189], v[48:63]
	v_mfma_f32_32x32x16_f16 v[32:47], v[178:181], v[186:189], v[32:47]
	s_waitcnt vmcnt(0)
	s_barrier
	s_add_u32 m0, s100, 1792
	s_nop 0
	global_load_lds_dwordx4 v[100:101], off offset:256
	s_add_u32 m0, s100, 5888
	s_nop 0
	global_load_lds_dwordx4 v[102:103], off offset:256
	s_add_u32 m0, s100, 9984
	s_nop 0
	global_load_lds_dwordx4 v[104:105], off offset:256
	s_add_u32 m0, s100, 14080
	s_nop 0
	global_load_lds_dwordx4 v[106:107], off offset:256
	s_add_u32 m0, s100, 18176
	s_nop 0
	global_load_lds_dwordx4 v[108:109], off offset:256
	s_add_u32 m0, s100, 22272
	s_nop 0
	global_load_lds_dwordx4 v[110:111], off offset:256
	ds_read_b128 v[178:181], v204 offset:41984
	ds_read_b128 v[182:185], v205 offset:41984
	ds_read_b128 v[186:189], v204 offset:46080
	ds_read_b128 v[190:193], v205 offset:46080
	ds_read_b128 v[194:197], v208 offset:58368
	ds_read_b128 v[198:201], v209 offset:58368
	s_waitcnt lgkmcnt(1)
	v_mfma_f32_32x32x16_f16 v[48:63], v[178:181], v[194:197], v[48:63]
	v_mfma_f32_32x32x16_f16 v[32:47], v[186:189], v[194:197], v[32:47]
	ds_read_b128 v[178:181], v206 offset:46080
	ds_read_b128 v[186:189], v206 offset:41984
	ds_read_b128 v[194:197], v210 offset:58368
	s_waitcnt lgkmcnt(3)
	v_mfma_f32_32x32x16_f16 v[48:63], v[182:185], v[198:201], v[48:63]
	v_mfma_f32_32x32x16_f16 v[32:47], v[190:193], v[198:201], v[32:47]
	ds_read_b128 v[182:185], v207 offset:46080
	ds_read_b128 v[190:193], v207 offset:41984
	ds_read_b128 v[198:201], v211 offset:58368
	s_waitcnt lgkmcnt(3)
	v_mfma_f32_32x32x16_f16 v[48:63], v[186:189], v[194:197], v[48:63]
	v_mfma_f32_32x32x16_f16 v[32:47], v[178:181], v[194:197], v[32:47]
	s_waitcnt lgkmcnt(0)
	v_mfma_f32_32x32x16_f16 v[48:63], v[190:193], v[198:201], v[48:63]
	v_mfma_f32_32x32x16_f16 v[32:47], v[182:185], v[198:201], v[32:47]
	s_waitcnt vmcnt(0)
	s_barrier
	s_add_u32 m0, s100, 41600
	s_nop 0
	global_load_lds_dwordx4 v[100:101], off offset:384
	s_add_u32 m0, s100, 45696
	s_nop 0
	global_load_lds_dwordx4 v[102:103], off offset:384
	s_add_u32 m0, s100, 49792
	s_nop 0
	global_load_lds_dwordx4 v[104:105], off offset:384
	s_add_u32 m0, s100, 53888
	s_nop 0
	global_load_lds_dwordx4 v[106:107], off offset:384
	s_add_u32 m0, s100, 57984
	s_nop 0
	global_load_lds_dwordx4 v[108:109], off offset:384
	s_add_u32 m0, s100, 62080
	s_nop 0
	global_load_lds_dwordx4 v[110:111], off offset:384
	ds_read_b128 v[178:181], v204 offset:2048
	ds_read_b128 v[182:185], v205 offset:2048
	ds_read_b128 v[186:189], v204 offset:6144
	ds_read_b128 v[190:193], v205 offset:6144
	ds_read_b128 v[194:197], v208 offset:18432
	ds_read_b128 v[198:201], v209 offset:18432
	s_waitcnt lgkmcnt(1)
	v_mfma_f32_32x32x16_f16 v[48:63], v[178:181], v[194:197], v[48:63]
	v_mfma_f32_32x32x16_f16 v[32:47], v[186:189], v[194:197], v[32:47]
	ds_read_b128 v[178:181], v206 offset:6144
	ds_read_b128 v[186:189], v206 offset:2048
	ds_read_b128 v[194:197], v210 offset:18432
	s_waitcnt lgkmcnt(3)
	v_mfma_f32_32x32x16_f16 v[48:63], v[182:185], v[198:201], v[48:63]
	v_mfma_f32_32x32x16_f16 v[32:47], v[190:193], v[198:201], v[32:47]
	ds_read_b128 v[182:185], v207 offset:6144
	ds_read_b128 v[190:193], v207 offset:2048
	ds_read_b128 v[198:201], v211 offset:18432
	s_waitcnt lgkmcnt(3)
	v_mfma_f32_32x32x16_f16 v[48:63], v[186:189], v[194:197], v[48:63]
	v_mfma_f32_32x32x16_f16 v[32:47], v[178:181], v[194:197], v[32:47]
	s_waitcnt lgkmcnt(0)
	v_mfma_f32_32x32x16_f16 v[48:63], v[190:193], v[198:201], v[48:63]
	v_mfma_f32_32x32x16_f16 v[32:47], v[182:185], v[198:201], v[32:47]
	s_waitcnt vmcnt(0)
	s_barrier
; #define G_LOAD(RA, RB, k_) do { \
;     _Pragma("unroll") for (int i = 0; i < 4; ++i) RA[i] = *(const u32x4*)&Ap[i * sa + (k_)]; \
;     _Pragma("unroll") for (int i = 0; i < 2 * NJ; ++i) RB[i] = *(const u32x4*)&Bp[i * sbb + (k_)]; } while (0)
; template <int NJ>
; DI void gemm_core(const h16* __restrict__ A, int lda, const h16* __restrict__ Bt, int ldb, int K,
;                   floatx16 (&acc)[2][NJ], h16* As, h16* Bs) {
;     ...
;   G_LOAD(ra0, rb0, 0);
;   if (64 < K) G_LOAD(ra1, rb1, 64);
;   for (int k0 = 0; k0 < K; k0 += 128) {
;     G_STEP(ra0, rb0, k0 + 128);
;     if (k0 + 64 < K) G_STEP(ra1, rb1, k0 + 192);
;   }
	s_add_u32 m0, s100, 1536
	s_nop 0
	global_load_lds_dwordx4 v[100:101], off offset:512
	s_add_u32 m0, s100, 5632
	s_nop 0
	global_load_lds_dwordx4 v[102:103], off offset:512
	s_add_u32 m0, s100, 9728
	s_nop 0
	global_load_lds_dwordx4 v[104:105], off offset:512
	s_add_u32 m0, s100, 13824
	s_nop 0
	global_load_lds_dwordx4 v[106:107], off offset:512
	s_add_u32 m0, s100, 17920
	s_nop 0
	global_load_lds_dwordx4 v[108:109], off offset:512
	s_add_u32 m0, s100, 22016
	s_nop 0
	global_load_lds_dwordx4 v[110:111], off offset:512
	ds_read_b128 v[178:181], v204 offset:41984
	ds_read_b128 v[182:185], v205 offset:41984
	ds_read_b128 v[186:189], v204 offset:46080
	ds_read_b128 v[190:193], v205 offset:46080
	ds_read_b128 v[194:197], v208 offset:58368
	ds_read_b128 v[198:201], v209 offset:58368
	s_waitcnt lgkmcnt(1)
	v_mfma_f32_32x32x16_f16 v[48:63], v[178:181], v[194:197], v[48:63]
	v_mfma_f32_32x32x16_f16 v[32:47], v[186:189], v[194:197], v[32:47]
	ds_read_b128 v[178:181], v206 offset:46080
	ds_read_b128 v[186:189], v206 offset:41984
	ds_read_b128 v[194:197], v210 offset:58368
	s_waitcnt lgkmcnt(3)
	v_mfma_f32_32x32x16_f16 v[48:63], v[182:185], v[198:201], v[48:63]
	v_mfma_f32_32x32x16_f16 v[32:47], v[190:193], v[198:201], v[32:47]
	ds_read_b128 v[182:185], v207 offset:46080
	ds_read_b128 v[190:193], v207 offset:41984
	ds_read_b128 v[198:201], v211 offset:58368
	s_waitcnt lgkmcnt(3)
	v_mfma_f32_32x32x16_f16 v[48:63], v[186:189], v[194:197], v[48:63]
	v_mfma_f32_32x32x16_f16 v[32:47], v[178:181], v[194:197], v[32:47]
	s_waitcnt lgkmcnt(0)
	v_mfma_f32_32x32x16_f16 v[48:63], v[190:193], v[198:201], v[48:63]
	v_mfma_f32_32x32x16_f16 v[32:47], v[182:185], v[198:201], v[32:47]
	s_waitcnt vmcnt(0)
	s_barrier
	s_add_u32 m0, s100, 41344
	s_nop 0
	global_load_lds_dwordx4 v[100:101], off offset:640
	s_add_u32 m0, s100, 45440
	s_nop 0
	global_load_lds_dwordx4 v[102:103], off offset:640
	s_add_u32 m0, s100, 49536
	s_nop 0
	global_load_lds_dwordx4 v[104:105], off offset:640
	s_add_u32 m0, s100, 53632
	s_nop 0
	global_load_lds_dwordx4 v[106:107], off offset:640
	s_add_u32 m0, s100, 57728
	s_nop 0
	global_load_lds_dwordx4 v[108:109], off offset:640
	s_add_u32 m0, s100, 61824
	s_nop 0
	global_load_lds_dwordx4 v[110:111], off offset:640
	ds_read_b128 v[178:181], v204 offset:2048
	ds_read_b128 v[182:185], v205 offset:2048
	ds_read_b128 v[186:189], v204 offset:6144
	ds_read_b128 v[190:193], v205 offset:6144
	ds_read_b128 v[194:197], v208 offset:18432
	ds_read_b128 v[198:201], v209 offset:18432
	s_waitcnt lgkmcnt(1)
	v_mfma_f32_32x32x16_f16 v[48:63], v[178:181], v[194:197], v[48:63]
	v_mfma_f32_32x32x16_f16 v[32:47], v[186:189], v[194:197], v[32:47]
	ds_read_b128 v[178:181], v206 offset:6144
	ds_read_b128 v[186:189], v206 offset:2048
	ds_read_b128 v[194:197], v210 offset:18432
	s_waitcnt lgkmcnt(3)
	v_mfma_f32_32x32x16_f16 v[48:63], v[182:185], v[198:201], v[48:63]
	v_mfma_f32_32x32x16_f16 v[32:47], v[190:193], v[198:201], v[32:47]
	ds_read_b128 v[182:185], v207 offset:6144
	ds_read_b128 v[190:193], v207 offset:2048
	ds_read_b128 v[198:201], v211 offset:18432
	s_waitcnt lgkmcnt(3)
	v_mfma_f32_32x32x16_f16 v[48:63], v[186:189], v[194:197], v[48:63]
	v_mfma_f32_32x32x16_f16 v[32:47], v[178:181], v[194:197], v[32:47]
	s_waitcnt lgkmcnt(0)
	v_mfma_f32_32x32x16_f16 v[48:63], v[190:193], v[198:201], v[48:63]
	v_mfma_f32_32x32x16_f16 v[32:47], v[182:185], v[198:201], v[32:47]
	s_waitcnt vmcnt(0)
	s_barrier
	s_add_u32 m0, s100, 1280
	s_nop 0
	global_load_lds_dwordx4 v[100:101], off offset:768
	s_add_u32 m0, s100, 5376
	s_nop 0
	global_load_lds_dwordx4 v[102:103], off offset:768
	s_add_u32 m0, s100, 9472
	s_nop 0
	global_load_lds_dwordx4 v[104:105], off offset:768
	s_add_u32 m0, s100, 13568
	s_nop 0
	global_load_lds_dwordx4 v[106:107], off offset:768
	s_add_u32 m0, s100, 17664
	s_nop 0
	global_load_lds_dwordx4 v[108:109], off offset:768
	s_add_u32 m0, s100, 21760
	s_nop 0
	global_load_lds_dwordx4 v[110:111], off offset:768
	s_nop 0
	s_nop 0
	s_nop 0
	s_nop 0
	s_nop 0
	ds_read_b128 v[124:127], v204 offset:41984
	ds_read_b128 v[128:131], v205 offset:41984
	ds_read_b128 v[134:137], v204 offset:46080
	ds_read_b128 v[178:181], v205 offset:46080
	ds_read_b128 v[182:185], v208 offset:58368
	ds_read_b128 v[186:189], v209 offset:58368
	s_waitcnt lgkmcnt(1)
	v_mfma_f32_32x32x16_f16 v[48:63], v[124:127], v[182:185], v[48:63]
	v_mfma_f32_32x32x16_f16 v[32:47], v[134:137], v[182:185], v[32:47]
	ds_read_b128 v[124:127], v206 offset:46080
	ds_read_b128 v[134:137], v206 offset:41984
	ds_read_b128 v[182:185], v210 offset:58368
	s_waitcnt lgkmcnt(3)
	v_mfma_f32_32x32x16_f16 v[48:63], v[128:131], v[186:189], v[48:63]
	v_mfma_f32_32x32x16_f16 v[32:47], v[178:181], v[186:189], v[32:47]
	ds_read_b128 v[128:131], v207 offset:46080
	ds_read_b128 v[178:181], v207 offset:41984
	ds_read_b128 v[186:189], v211 offset:58368
	s_waitcnt lgkmcnt(3)
	v_mfma_f32_32x32x16_f16 v[48:63], v[134:137], v[182:185], v[48:63]
	v_mfma_f32_32x32x16_f16 v[32:47], v[124:127], v[182:185], v[32:47]
	s_waitcnt lgkmcnt(0)
	v_mfma_f32_32x32x16_f16 v[48:63], v[178:181], v[186:189], v[48:63]
	v_mfma_f32_32x32x16_f16 v[32:47], v[128:131], v[186:189], v[32:47]
	s_waitcnt vmcnt(0)
	s_barrier
; DI float sigmoidf_(float x) { return __builtin_amdgcn_rcpf(1.f + __expf(-x)); }
; #define G_LOAD(RA, RB, k_) do { \
;     _Pragma("unroll") for (int i = 0; i < 4; ++i) RA[i] = *(const u32x4*)&Ap[i * sa + (k_)]; \
;     _Pragma("unroll") for (int i = 0; i < 2 * NJ; ++i) RB[i] = *(const u32x4*)&Bp[i * sbb + (k_)]; } while (0)
; template <int NJ>
; DI void gemm_core(const h16* __restrict__ A, int lda, const h16* __restrict__ Bt, int ldb, int K,
;                   floatx16 (&acc)[2][NJ], h16* As, h16* Bs) {
;     ...
;   G_LOAD(ra0, rb0, 0);
;   if (64 < K) G_LOAD(ra1, rb1, 64);
;   for (int k0 = 0; k0 < K; k0 += 128) {
;     G_STEP(ra0, rb0, k0 + 128);
;     if (k0 + 64 < K) G_STEP(ra1, rb1, k0 + 192);
;   }
; __global__ void __launch_bounds__(256, 2) mega(Params p) {
;     ...
; #pragma unroll
;         for (int i = 0; i < 2; ++i)
; #pragma unroll
;           for (int r = 0; r < 16; ++r) mg[i][0][r] += sigmoidf_(ag[i][0][r]) * ap[i][0][r];
	s_add_u32 m0, s100, 41088
	s_nop 0
	global_load_lds_dwordx4 v[100:101], off offset:896
	s_add_u32 m0, s100, 45184
	s_nop 0
	global_load_lds_dwordx4 v[102:103], off offset:896
	s_add_u32 m0, s100, 49280
	s_nop 0
	global_load_lds_dwordx4 v[104:105], off offset:896
	s_add_u32 m0, s100, 53376
	s_nop 0
	global_load_lds_dwordx4 v[106:107], off offset:896
	s_add_u32 m0, s100, 57472
	s_nop 0
	global_load_lds_dwordx4 v[108:109], off offset:896
	s_add_u32 m0, s100, 61568
	s_nop 0
	global_load_lds_dwordx4 v[110:111], off offset:896
	ds_read_b128 v[124:127], v204 offset:2048
	ds_read_b128 v[128:131], v205 offset:2048
	ds_read_b128 v[134:137], v204 offset:6144
	ds_read_b128 v[138:141], v205 offset:6144
	ds_read_b128 v[142:145], v208 offset:18432
	ds_read_b128 v[146:149], v209 offset:18432
	s_waitcnt lgkmcnt(1)
	v_mfma_f32_32x32x16_f16 v[48:63], v[124:127], v[142:145], v[48:63]
	v_mfma_f32_32x32x16_f16 v[32:47], v[134:137], v[142:145], v[32:47]
	ds_read_b128 v[124:127], v206 offset:6144
	ds_read_b128 v[134:137], v206 offset:2048
	ds_read_b128 v[142:145], v210 offset:18432
	s_waitcnt lgkmcnt(3)
	v_mfma_f32_32x32x16_f16 v[48:63], v[128:131], v[146:149], v[48:63]
	v_mfma_f32_32x32x16_f16 v[32:47], v[138:141], v[146:149], v[32:47]
	ds_read_b128 v[128:131], v207 offset:6144
	ds_read_b128 v[138:141], v207 offset:2048
	ds_read_b128 v[146:149], v211 offset:18432
	s_waitcnt lgkmcnt(3)
	v_mfma_f32_32x32x16_f16 v[48:63], v[134:137], v[142:145], v[48:63]
	v_mfma_f32_32x32x16_f16 v[32:47], v[124:127], v[142:145], v[32:47]
	s_waitcnt lgkmcnt(0)
	v_mfma_f32_32x32x16_f16 v[48:63], v[138:141], v[146:149], v[48:63]
	v_mfma_f32_32x32x16_f16 v[32:47], v[128:131], v[146:149], v[32:47]
	s_waitcnt vmcnt(0)
	s_barrier
	ds_read_b128 v[100:103], v204 offset:41984
	ds_read_b128 v[104:107], v205 offset:41984
	ds_read_b128 v[108:111], v204 offset:46080
	ds_read_b128 v[112:115], v205 offset:46080
	ds_read_b128 v[116:119], v208 offset:58368
	ds_read_b128 v[120:123], v209 offset:58368
	s_waitcnt lgkmcnt(1)
	v_mfma_f32_32x32x16_f16 v[48:63], v[100:103], v[116:119], v[48:63]
	v_mfma_f32_32x32x16_f16 v[32:47], v[108:111], v[116:119], v[32:47]
	ds_read_b128 v[100:103], v206 offset:46080
	ds_read_b128 v[108:111], v206 offset:41984
	ds_read_b128 v[116:119], v210 offset:58368
	s_waitcnt lgkmcnt(3)
	v_mfma_f32_32x32x16_f16 v[48:63], v[104:107], v[120:123], v[48:63]
	v_mfma_f32_32x32x16_f16 v[32:47], v[112:115], v[120:123], v[32:47]
	ds_read_b128 v[104:107], v207 offset:46080
	ds_read_b128 v[96:99], v207 offset:41984
	ds_read_b128 v[112:115], v211 offset:58368
	s_waitcnt lgkmcnt(3)
	v_mfma_f32_32x32x16_f16 v[48:63], v[108:111], v[116:119], v[48:63]
	v_mfma_f32_32x32x16_f16 v[32:47], v[100:103], v[116:119], v[32:47]
	s_waitcnt lgkmcnt(0)
	v_mfma_f32_32x32x16_f16 v[48:63], v[96:99], v[112:115], v[48:63]
	v_mfma_f32_32x32x16_f16 v[32:47], v[104:107], v[112:115], v[32:47]
	v_mul_f32_e32 v16, 0xbfb8aa3b, v16
	v_mul_f32_e32 v17, 0xbfb8aa3b, v17
	v_mul_f32_e32 v0, 0xbfb8aa3b, v0
	v_mul_f32_e32 v1, 0xbfb8aa3b, v1
	v_exp_f32_e32 v16, v16
	v_exp_f32_e32 v17, v17
	v_exp_f32_e32 v0, v0
	v_exp_f32_e32 v1, v1
	v_add_f32_e32 v16, 1.0, v16
	v_add_f32_e32 v17, 1.0, v17
	v_mul_f32_e32 v18, 0xbfb8aa3b, v18
	v_mul_f32_e32 v19, 0xbfb8aa3b, v19
	v_add_f32_e32 v0, 1.0, v0
	v_add_f32_e32 v1, 1.0, v1
	v_mul_f32_e32 v2, 0xbfb8aa3b, v2
	v_mul_f32_e32 v3, 0xbfb8aa3b, v3
	v_rcp_f32_e32 v16, v16
	v_rcp_f32_e32 v17, v17
	v_exp_f32_e32 v18, v18
	v_exp_f32_e32 v19, v19
	v_rcp_f32_e32 v0, v0
	v_rcp_f32_e32 v1, v1
	v_exp_f32_e32 v2, v2
	v_exp_f32_e32 v3, v3
	v_pk_fma_f32 v[94:95], v[16:17], v[48:49], v[94:95]
	v_add_f32_e32 v16, 1.0, v18
	v_add_f32_e32 v17, 1.0, v19
	v_mul_f32_e32 v18, 0xbfb8aa3b, v20
	v_mul_f32_e32 v19, 0xbfb8aa3b, v21
	v_pk_fma_f32 v[78:79], v[0:1], v[32:33], v[78:79]
	v_add_f32_e32 v0, 1.0, v2
	v_add_f32_e32 v1, 1.0, v3
	v_mul_f32_e32 v2, 0xbfb8aa3b, v4
	v_mul_f32_e32 v3, 0xbfb8aa3b, v5
	v_rcp_f32_e32 v16, v16
	v_rcp_f32_e32 v17, v17
	v_exp_f32_e32 v18, v18
	v_exp_f32_e32 v19, v19
	v_rcp_f32_e32 v0, v0
	v_rcp_f32_e32 v1, v1
	v_exp_f32_e32 v2, v2
	v_exp_f32_e32 v3, v3
	v_pk_fma_f32 v[92:93], v[16:17], v[50:51], v[92:93]
	v_add_f32_e32 v16, 1.0, v18
	v_add_f32_e32 v17, 1.0, v19
	v_mul_f32_e32 v18, 0xbfb8aa3b, v22
	v_mul_f32_e32 v19, 0xbfb8aa3b, v23
	v_pk_fma_f32 v[76:77], v[0:1], v[34:35], v[76:77]
	v_add_f32_e32 v0, 1.0, v2
	v_add_f32_e32 v1, 1.0, v3
	v_mul_f32_e32 v2, 0xbfb8aa3b, v6
	v_mul_f32_e32 v3, 0xbfb8aa3b, v7
	v_rcp_f32_e32 v16, v16
	v_rcp_f32_e32 v17, v17
	v_exp_f32_e32 v18, v18
	v_exp_f32_e32 v19, v19
	v_rcp_f32_e32 v0, v0
	v_rcp_f32_e32 v1, v1
	v_exp_f32_e32 v2, v2
	v_exp_f32_e32 v3, v3
	v_pk_fma_f32 v[90:91], v[16:17], v[52:53], v[90:91]
	v_add_f32_e32 v16, 1.0, v18
	v_add_f32_e32 v17, 1.0, v19
	v_mul_f32_e32 v18, 0xbfb8aa3b, v24
	v_mul_f32_e32 v19, 0xbfb8aa3b, v25
	v_pk_fma_f32 v[74:75], v[0:1], v[36:37], v[74:75]
	v_add_f32_e32 v0, 1.0, v2
	v_add_f32_e32 v1, 1.0, v3
	v_mul_f32_e32 v2, 0xbfb8aa3b, v8
	v_mul_f32_e32 v3, 0xbfb8aa3b, v9
	v_rcp_f32_e32 v16, v16
	v_rcp_f32_e32 v17, v17
	v_exp_f32_e32 v18, v18
	v_exp_f32_e32 v19, v19
	v_rcp_f32_e32 v0, v0
	v_rcp_f32_e32 v1, v1
	v_exp_f32_e32 v2, v2
	v_exp_f32_e32 v3, v3
	v_pk_fma_f32 v[88:89], v[16:17], v[54:55], v[88:89]
	v_add_f32_e32 v16, 1.0, v18
	v_add_f32_e32 v17, 1.0, v19
	v_mul_f32_e32 v18, 0xbfb8aa3b, v26
	v_mul_f32_e32 v19, 0xbfb8aa3b, v27
	v_pk_fma_f32 v[72:73], v[0:1], v[38:39], v[72:73]
	v_add_f32_e32 v0, 1.0, v2
	v_add_f32_e32 v1, 1.0, v3
	v_mul_f32_e32 v2, 0xbfb8aa3b, v10
	v_mul_f32_e32 v3, 0xbfb8aa3b, v11
	v_rcp_f32_e32 v16, v16
	v_rcp_f32_e32 v17, v17
	v_exp_f32_e32 v18, v18
	v_exp_f32_e32 v19, v19
	v_rcp_f32_e32 v0, v0
; DI float sigmoidf_(float x) { return __builtin_amdgcn_rcpf(1.f + __expf(-x)); }
; __global__ void __launch_bounds__(256, 2) mega(Params p) {
;     ...
; #pragma unroll
;         for (int i = 0; i < 2; ++i)
; #pragma unroll
;           for (int r = 0; r < 16; ++r) mg[i][0][r] += sigmoidf_(ag[i][0][r]) * ap[i][0][r];
;       }
;       epi_apply<1>(mg, [&](int r, int c, float v) { merged[(size_t)(m0 + r) * 1024 + n0 + c] = (h16)v; });
	v_rcp_f32_e32 v1, v1
	v_exp_f32_e32 v2, v2
	v_exp_f32_e32 v3, v3
	v_pk_fma_f32 v[86:87], v[16:17], v[56:57], v[86:87]
	v_add_f32_e32 v16, 1.0, v18
	v_add_f32_e32 v17, 1.0, v19
	v_mul_f32_e32 v18, 0xbfb8aa3b, v28
	v_mul_f32_e32 v19, 0xbfb8aa3b, v29
	v_pk_fma_f32 v[70:71], v[0:1], v[40:41], v[70:71]
	v_add_f32_e32 v0, 1.0, v2
	v_add_f32_e32 v1, 1.0, v3
	v_mul_f32_e32 v2, 0xbfb8aa3b, v12
	v_mul_f32_e32 v3, 0xbfb8aa3b, v13
	v_rcp_f32_e32 v16, v16
	v_rcp_f32_e32 v17, v17
	v_exp_f32_e32 v18, v18
	v_exp_f32_e32 v19, v19
	v_rcp_f32_e32 v0, v0
	v_rcp_f32_e32 v1, v1
	v_exp_f32_e32 v2, v2
	v_exp_f32_e32 v3, v3
	v_pk_fma_f32 v[84:85], v[16:17], v[58:59], v[84:85]
	v_add_f32_e32 v16, 1.0, v18
	v_add_f32_e32 v17, 1.0, v19
	v_mul_f32_e32 v18, 0xbfb8aa3b, v30
	v_mul_f32_e32 v19, 0xbfb8aa3b, v31
	v_pk_fma_f32 v[68:69], v[0:1], v[42:43], v[68:69]
	v_add_f32_e32 v0, 1.0, v2
	v_add_f32_e32 v1, 1.0, v3
	v_mul_f32_e32 v2, 0xbfb8aa3b, v14
	v_mul_f32_e32 v3, 0xbfb8aa3b, v15
	v_rcp_f32_e32 v16, v16
	v_rcp_f32_e32 v17, v17
	v_exp_f32_e32 v18, v18
	v_exp_f32_e32 v19, v19
	v_rcp_f32_e32 v0, v0
	v_rcp_f32_e32 v1, v1
	v_exp_f32_e32 v2, v2
	v_exp_f32_e32 v3, v3
	v_pk_fma_f32 v[82:83], v[16:17], v[60:61], v[82:83]
	v_add_f32_e32 v16, 1.0, v18
	v_add_f32_e32 v17, 1.0, v19
	v_pk_fma_f32 v[66:67], v[0:1], v[44:45], v[66:67]
	v_add_f32_e32 v0, 1.0, v2
	v_add_f32_e32 v1, 1.0, v3
	s_add_i32 s64, s64, 1
	v_rcp_f32_e32 v16, v16
	v_rcp_f32_e32 v17, v17
	v_rcp_f32_e32 v0, v0
	v_rcp_f32_e32 v1, v1
	s_add_u32 s44, s44, 0x100000
	s_addc_u32 s45, s45, 0
	s_add_u32 s47, s47, 0x200000
	s_addc_u32 s53, s53, 0
	v_pk_fma_f32 v[80:81], v[16:17], v[62:63], v[80:81]
	s_cmp_eq_u32 s64, 3
	v_pk_fma_f32 v[64:65], v[0:1], v[46:47], v[64:65]
	s_cbranch_scc0 .LBB0_984
	v_mov_b32_e32 v0, v152
	s_and_b32 s42, s60, 8
	v_ashrrev_i32_e32 v2, 1, v0
	v_and_b32_e32 v1, 31, v0
	v_and_b32_e32 v2, 0xffffffc0, v2
	v_lshrrev_b32_e32 v3, 3, v0
	v_lshrrev_b32_e32 v0, 1, v0
	v_and_or_b32 v4, v0, 32, v1
	v_and_or_b32 v0, v3, 4, v2
	v_add_u32_e32 v0, s46, v0
	s_and_b32 s43, s41, 7
	v_ashrrev_i32_e32 v1, 31, v0
	s_or_b32 s42, s42, s43
	v_cvt_f16_f32_e32 v5, v94
	v_lshlrev_b64 v[2:3], 11, v[0:1]
	v_lshl_add_u64 v[2:3], s[36:37], 0, v[2:3]
	s_lshl_b32 s76, s42, 7
	v_lshl_add_u64 v[2:3], v[2:3], 0, s[76:77]
	v_lshlrev_b32_e32 v132, 1, v4
	v_lshl_add_u64 v[2:3], v[2:3], 0, v[132:133]
	global_store_short v[2:3], v5, off
	v_add_u32_e32 v2, 1, v0
	v_ashrrev_i32_e32 v3, 31, v2
	v_cvt_f16_f32_e32 v1, v95
	v_lshlrev_b64 v[2:3], 11, v[2:3]
	v_lshl_add_u64 v[2:3], s[36:37], 0, v[2:3]
	v_lshl_add_u64 v[2:3], v[2:3], 0, s[76:77]
	v_lshl_add_u64 v[2:3], v[2:3], 0, v[132:133]
	global_store_short v[2:3], v1, off
	v_add_u32_e32 v2, 2, v0
	v_ashrrev_i32_e32 v3, 31, v2
	v_cvt_f16_f32_e32 v1, v92
	v_lshlrev_b64 v[2:3], 11, v[2:3]
	v_lshl_add_u64 v[2:3], s[36:37], 0, v[2:3]
	v_lshl_add_u64 v[2:3], v[2:3], 0, s[76:77]
	v_lshl_add_u64 v[2:3], v[2:3], 0, v[132:133]
	global_store_short v[2:3], v1, off
	v_add_u32_e32 v2, 3, v0
	v_ashrrev_i32_e32 v3, 31, v2
	v_cvt_f16_f32_e32 v1, v93
	v_lshlrev_b64 v[2:3], 11, v[2:3]
	v_lshl_add_u64 v[2:3], s[36:37], 0, v[2:3]
	v_lshl_add_u64 v[2:3], v[2:3], 0, s[76:77]
	s_mov_b32 s35, 0xfffffc0
	s_mov_b32 s33, 0x30000
	s_mov_b32 s59, 0x20000
	v_lshl_add_u64 v[2:3], v[2:3], 0, v[132:133]
	global_store_short v[2:3], v1, off
	v_add_u32_e32 v2, 8, v0
	v_ashrrev_i32_e32 v3, 31, v2
	v_cvt_f16_f32_e32 v1, v90
	v_lshlrev_b64 v[2:3], 11, v[2:3]
	v_lshl_add_u64 v[2:3], s[36:37], 0, v[2:3]
	v_lshl_add_u64 v[2:3], v[2:3], 0, s[76:77]
	v_lshl_add_u64 v[2:3], v[2:3], 0, v[132:133]
	global_store_short v[2:3], v1, off
	v_add_u32_e32 v2, 9, v0
	v_ashrrev_i32_e32 v3, 31, v2
	v_cvt_f16_f32_e32 v1, v91
	v_lshlrev_b64 v[2:3], 11, v[2:3]
	v_lshl_add_u64 v[2:3], s[36:37], 0, v[2:3]
	v_lshl_add_u64 v[2:3], v[2:3], 0, s[76:77]
	v_lshl_add_u64 v[2:3], v[2:3], 0, v[132:133]
	global_store_short v[2:3], v1, off
	v_add_u32_e32 v2, 10, v0
	v_ashrrev_i32_e32 v3, 31, v2
	v_cvt_f16_f32_e32 v1, v88
	v_lshlrev_b64 v[2:3], 11, v[2:3]
	v_lshl_add_u64 v[2:3], s[36:37], 0, v[2:3]
	v_lshl_add_u64 v[2:3], v[2:3], 0, s[76:77]
	v_lshl_add_u64 v[2:3], v[2:3], 0, v[132:133]
	global_store_short v[2:3], v1, off
	v_add_u32_e32 v2, 11, v0
	v_ashrrev_i32_e32 v3, 31, v2
	v_cvt_f16_f32_e32 v1, v89
	v_lshlrev_b64 v[2:3], 11, v[2:3]
	v_lshl_add_u64 v[2:3], s[36:37], 0, v[2:3]
	v_lshl_add_u64 v[2:3], v[2:3], 0, s[76:77]
	v_lshl_add_u64 v[2:3], v[2:3], 0, v[132:133]
	global_store_short v[2:3], v1, off
	v_add_u32_e32 v2, 16, v0
	v_ashrrev_i32_e32 v3, 31, v2
	v_cvt_f16_f32_e32 v1, v86
	v_lshlrev_b64 v[2:3], 11, v[2:3]
	v_lshl_add_u64 v[2:3], s[36:37], 0, v[2:3]
	v_lshl_add_u64 v[2:3], v[2:3], 0, s[76:77]
	v_lshl_add_u64 v[2:3], v[2:3], 0, v[132:133]
	global_store_short v[2:3], v1, off
	v_add_u32_e32 v2, 17, v0
	v_ashrrev_i32_e32 v3, 31, v2
	v_cvt_f16_f32_e32 v1, v87
	v_lshlrev_b64 v[2:3], 11, v[2:3]
	v_lshl_add_u64 v[2:3], s[36:37], 0, v[2:3]
	v_lshl_add_u64 v[2:3], v[2:3], 0, s[76:77]
	v_lshl_add_u64 v[2:3], v[2:3], 0, v[132:133]
	global_store_short v[2:3], v1, off
	v_add_u32_e32 v2, 18, v0
	v_ashrrev_i32_e32 v3, 31, v2
	v_cvt_f16_f32_e32 v1, v84
	v_lshlrev_b64 v[2:3], 11, v[2:3]
	v_lshl_add_u64 v[2:3], s[36:37], 0, v[2:3]
	v_lshl_add_u64 v[2:3], v[2:3], 0, s[76:77]
	v_lshl_add_u64 v[2:3], v[2:3], 0, v[132:133]
	global_store_short v[2:3], v1, off
	v_add_u32_e32 v2, 19, v0
	v_ashrrev_i32_e32 v3, 31, v2
	v_cvt_f16_f32_e32 v1, v85
	v_lshlrev_b64 v[2:3], 11, v[2:3]
	v_lshl_add_u64 v[2:3], s[36:37], 0, v[2:3]
	v_lshl_add_u64 v[2:3], v[2:3], 0, s[76:77]
	v_lshl_add_u64 v[2:3], v[2:3], 0, v[132:133]
	global_store_short v[2:3], v1, off
	v_add_u32_e32 v2, 24, v0
; DI int otid() { int t = threadIdx.x; asm volatile("" : "+v"(t)); return t; }
; template <int NJ, class F>
; DI void epi_apply(const floatx16 (&acc)[2][NJ], F f) {
;   const int t = otid(), l = t & 63, w = t >> 6, wm = w >> 1, wn = w & 1, h = l >> 5, lr = l & 31;
; #pragma unroll
;   for (int i = 0; i < 2; ++i)
; #pragma unroll
;     for (int j = 0; j < NJ; ++j)
; #pragma unroll
;       for (int r = 0; r < 16; ++r) {
;         f(wm * 64 + i * 32 + (r & 3) + 8 * (r >> 2) + 4 * h, wn * 32 * NJ + j * 32 + lr, acc[i][j][r]);
;         if ((r & 3) == 3) __builtin_amdgcn_sched_barrier(0);
;       }
; __global__ void __launch_bounds__(256, 2) mega(Params p) {
;     ...
;       epi_apply<1>(mg, [&](int r, int c, float v) { merged[(size_t)(m0 + r) * 1024 + n0 + c] = (h16)v; });
;     }
	v_ashrrev_i32_e32 v3, 31, v2
	v_cvt_f16_f32_e32 v1, v82
	v_lshlrev_b64 v[2:3], 11, v[2:3]
	v_lshl_add_u64 v[2:3], s[36:37], 0, v[2:3]
	v_lshl_add_u64 v[2:3], v[2:3], 0, s[76:77]
	v_lshl_add_u64 v[2:3], v[2:3], 0, v[132:133]
	global_store_short v[2:3], v1, off
	v_add_u32_e32 v2, 25, v0
	v_ashrrev_i32_e32 v3, 31, v2
	v_cvt_f16_f32_e32 v1, v83
	v_lshlrev_b64 v[2:3], 11, v[2:3]
	v_lshl_add_u64 v[2:3], s[36:37], 0, v[2:3]
	v_lshl_add_u64 v[2:3], v[2:3], 0, s[76:77]
	v_lshl_add_u64 v[2:3], v[2:3], 0, v[132:133]
	global_store_short v[2:3], v1, off
	v_add_u32_e32 v2, 26, v0
	v_ashrrev_i32_e32 v3, 31, v2
	v_cvt_f16_f32_e32 v1, v80
	v_lshlrev_b64 v[2:3], 11, v[2:3]
	v_lshl_add_u64 v[2:3], s[36:37], 0, v[2:3]
	v_lshl_add_u64 v[2:3], v[2:3], 0, s[76:77]
	v_lshl_add_u64 v[2:3], v[2:3], 0, v[132:133]
	global_store_short v[2:3], v1, off
	v_add_u32_e32 v2, 27, v0
	v_ashrrev_i32_e32 v3, 31, v2
	v_cvt_f16_f32_e32 v1, v81
	v_lshlrev_b64 v[2:3], 11, v[2:3]
	v_lshl_add_u64 v[2:3], s[36:37], 0, v[2:3]
	v_lshl_add_u64 v[2:3], v[2:3], 0, s[76:77]
	v_lshl_add_u64 v[2:3], v[2:3], 0, v[132:133]
	global_store_short v[2:3], v1, off
	v_add_u32_e32 v2, 32, v0
	v_ashrrev_i32_e32 v3, 31, v2
	v_cvt_f16_f32_e32 v1, v78
	v_lshlrev_b64 v[2:3], 11, v[2:3]
	v_lshl_add_u64 v[2:3], s[36:37], 0, v[2:3]
	v_lshl_add_u64 v[2:3], v[2:3], 0, s[76:77]
	v_lshl_add_u64 v[2:3], v[2:3], 0, v[132:133]
	global_store_short v[2:3], v1, off
	v_add_u32_e32 v2, 33, v0
	v_ashrrev_i32_e32 v3, 31, v2
	v_cvt_f16_f32_e32 v1, v79
	v_lshlrev_b64 v[2:3], 11, v[2:3]
	v_lshl_add_u64 v[2:3], s[36:37], 0, v[2:3]
	v_lshl_add_u64 v[2:3], v[2:3], 0, s[76:77]
	v_lshl_add_u64 v[2:3], v[2:3], 0, v[132:133]
	global_store_short v[2:3], v1, off
	v_add_u32_e32 v2, 34, v0
	v_ashrrev_i32_e32 v3, 31, v2
	v_cvt_f16_f32_e32 v1, v76
	v_lshlrev_b64 v[2:3], 11, v[2:3]
	v_lshl_add_u64 v[2:3], s[36:37], 0, v[2:3]
	v_lshl_add_u64 v[2:3], v[2:3], 0, s[76:77]
	v_lshl_add_u64 v[2:3], v[2:3], 0, v[132:133]
	global_store_short v[2:3], v1, off
	v_add_u32_e32 v2, 35, v0
	v_ashrrev_i32_e32 v3, 31, v2
	v_cvt_f16_f32_e32 v1, v77
	v_lshlrev_b64 v[2:3], 11, v[2:3]
	v_lshl_add_u64 v[2:3], s[36:37], 0, v[2:3]
	v_lshl_add_u64 v[2:3], v[2:3], 0, s[76:77]
	v_lshl_add_u64 v[2:3], v[2:3], 0, v[132:133]
	global_store_short v[2:3], v1, off
	v_add_u32_e32 v2, 40, v0
	v_ashrrev_i32_e32 v3, 31, v2
	v_cvt_f16_f32_e32 v1, v74
	v_lshlrev_b64 v[2:3], 11, v[2:3]
	v_lshl_add_u64 v[2:3], s[36:37], 0, v[2:3]
	v_lshl_add_u64 v[2:3], v[2:3], 0, s[76:77]
	v_lshl_add_u64 v[2:3], v[2:3], 0, v[132:133]
	global_store_short v[2:3], v1, off
	v_add_u32_e32 v2, 41, v0
	v_ashrrev_i32_e32 v3, 31, v2
	v_cvt_f16_f32_e32 v1, v75
	v_lshlrev_b64 v[2:3], 11, v[2:3]
	v_lshl_add_u64 v[2:3], s[36:37], 0, v[2:3]
	v_lshl_add_u64 v[2:3], v[2:3], 0, s[76:77]
	v_lshl_add_u64 v[2:3], v[2:3], 0, v[132:133]
	global_store_short v[2:3], v1, off
	v_add_u32_e32 v2, 42, v0
	v_ashrrev_i32_e32 v3, 31, v2
	v_cvt_f16_f32_e32 v1, v72
	v_lshlrev_b64 v[2:3], 11, v[2:3]
	v_lshl_add_u64 v[2:3], s[36:37], 0, v[2:3]
	v_lshl_add_u64 v[2:3], v[2:3], 0, s[76:77]
	v_lshl_add_u64 v[2:3], v[2:3], 0, v[132:133]
	global_store_short v[2:3], v1, off
	v_add_u32_e32 v2, 43, v0
	v_ashrrev_i32_e32 v3, 31, v2
	v_cvt_f16_f32_e32 v1, v73
	v_lshlrev_b64 v[2:3], 11, v[2:3]
	v_lshl_add_u64 v[2:3], s[36:37], 0, v[2:3]
	v_lshl_add_u64 v[2:3], v[2:3], 0, s[76:77]
	v_lshl_add_u64 v[2:3], v[2:3], 0, v[132:133]
	global_store_short v[2:3], v1, off
	v_add_u32_e32 v2, 48, v0
	v_ashrrev_i32_e32 v3, 31, v2
	v_cvt_f16_f32_e32 v1, v70
	v_lshlrev_b64 v[2:3], 11, v[2:3]
	v_lshl_add_u64 v[2:3], s[36:37], 0, v[2:3]
	v_lshl_add_u64 v[2:3], v[2:3], 0, s[76:77]
	v_lshl_add_u64 v[2:3], v[2:3], 0, v[132:133]
	global_store_short v[2:3], v1, off
	v_add_u32_e32 v2, 49, v0
	v_ashrrev_i32_e32 v3, 31, v2
	v_cvt_f16_f32_e32 v1, v71
	v_lshlrev_b64 v[2:3], 11, v[2:3]
	v_lshl_add_u64 v[2:3], s[36:37], 0, v[2:3]
	v_lshl_add_u64 v[2:3], v[2:3], 0, s[76:77]
	v_lshl_add_u64 v[2:3], v[2:3], 0, v[132:133]
	global_store_short v[2:3], v1, off
	v_add_u32_e32 v2, 50, v0
	v_ashrrev_i32_e32 v3, 31, v2
	v_cvt_f16_f32_e32 v1, v68
	v_lshlrev_b64 v[2:3], 11, v[2:3]
	v_lshl_add_u64 v[2:3], s[36:37], 0, v[2:3]
	v_lshl_add_u64 v[2:3], v[2:3], 0, s[76:77]
	v_lshl_add_u64 v[2:3], v[2:3], 0, v[132:133]
	global_store_short v[2:3], v1, off
	v_add_u32_e32 v2, 51, v0
	v_ashrrev_i32_e32 v3, 31, v2
	v_cvt_f16_f32_e32 v1, v69
	v_lshlrev_b64 v[2:3], 11, v[2:3]
	v_lshl_add_u64 v[2:3], s[36:37], 0, v[2:3]
	v_lshl_add_u64 v[2:3], v[2:3], 0, s[76:77]
	v_lshl_add_u64 v[2:3], v[2:3], 0, v[132:133]
	global_store_short v[2:3], v1, off
	v_add_u32_e32 v2, 56, v0
	v_ashrrev_i32_e32 v3, 31, v2
	v_cvt_f16_f32_e32 v1, v66
	v_lshlrev_b64 v[2:3], 11, v[2:3]
	v_lshl_add_u64 v[2:3], s[36:37], 0, v[2:3]
	v_lshl_add_u64 v[2:3], v[2:3], 0, s[76:77]
	v_lshl_add_u64 v[2:3], v[2:3], 0, v[132:133]
	global_store_short v[2:3], v1, off
	v_add_u32_e32 v2, 57, v0
	v_ashrrev_i32_e32 v3, 31, v2
	v_cvt_f16_f32_e32 v1, v67
	v_lshlrev_b64 v[2:3], 11, v[2:3]
	v_lshl_add_u64 v[2:3], s[36:37], 0, v[2:3]
	v_lshl_add_u64 v[2:3], v[2:3], 0, s[76:77]
	v_lshl_add_u64 v[2:3], v[2:3], 0, v[132:133]
	global_store_short v[2:3], v1, off
	v_add_u32_e32 v2, 58, v0
	v_ashrrev_i32_e32 v3, 31, v2
	v_cvt_f16_f32_e32 v1, v64
	v_lshlrev_b64 v[2:3], 11, v[2:3]
	v_lshl_add_u64 v[2:3], s[36:37], 0, v[2:3]
	v_lshl_add_u64 v[2:3], v[2:3], 0, s[76:77]
	v_lshl_add_u64 v[2:3], v[2:3], 0, v[132:133]
	v_add_u32_e32 v0, 59, v0
	global_store_short v[2:3], v1, off
	v_ashrrev_i32_e32 v1, 31, v0
	v_cvt_f16_f32_e32 v2, v65
	v_lshlrev_b64 v[0:1], 11, v[0:1]
	v_lshl_add_u64 v[0:1], s[36:37], 0, v[0:1]
	v_lshl_add_u64 v[0:1], v[0:1], 0, s[76:77]
	v_lshl_add_u64 v[0:1], v[0:1], 0, v[132:133]
	global_store_short v[0:1], v2, off
	s_add_i32 s41, s41, s34
	s_add_i32 s40, s40, s34
	s_cmpk_gt_u32 s41, 0x3ff
	s_cbranch_scc0 .LBB0_983
